# v145 plus check-free fast trip loops in front of the general loops (run while at least four tiles remain), far-branch islands for the grown code
# speedup vs baseline: 1.0001x; 1.0001x over previous
.LBF1_top:
	s_cmp_ge_i32 s65, s69
	s_cbranch_scc1 .LB1_top
	s_mov_b32 m0, s32
	s_add_u32 s80, s80, 0x20000
	s_addc_u32 s81, s81, 0
	global_load_lds_dwordx4 v128, s[80:81]
	s_add_i32 m0, m0, 0x2000
	s_nop 0
	global_load_lds_dwordx4 v129, s[80:81]
	s_add_i32 m0, s32, 0x12800
	s_nop 0
	global_load_lds_dwordx4 v130, s[80:81]
	s_add_i32 m0, m0, 0x2000
	s_nop 0
	global_load_lds_dwordx4 v131, s[80:81]
	s_mov_b32 m0, s5
	s_nop 0
	global_load_lds_dwordx4 v132, s[80:81]
	v_max_f32_e32 v176, v96, v80
	v_max3_f32 v177, v81, v98, v82
	v_max3_f32 v176, v176, v97, v99
	v_max3_f32 v177, v177, v100, v84
	v_max3_f32 v176, v176, v83, v101
	v_max3_f32 v177, v177, v102, v86
	v_max3_f32 v176, v176, v85, v103
	v_max3_f32 v177, v177, v104, v88
	v_max3_f32 v176, v176, v87, v105
	v_max3_f32 v177, v177, v106, v90
	v_max3_f32 v176, v176, v89, v107
	v_max3_f32 v177, v177, v108, v92
	v_max3_f32 v176, v176, v91, v109
	v_max3_f32 v177, v177, v110, v94
	v_max3_f32 v176, v176, v93, v111
	v_max3_f32 v176, v176, v95, v177
	v_cmp_lt_f32_e32 vcc, 0x41000000, v176
	s_cbranch_vccnz .Lrs_bf1
.Latt_bf1_exp:
	v_exp_f32_e32 v96, v96
	v_exp_f32_e32 v97, v97
	v_exp_f32_e32 v176, v80
	v_exp_f32_e32 v177, v81
	v_exp_f32_e32 v98, v98
	v_exp_f32_e32 v99, v99
	v_exp_f32_e32 v178, v82
	v_exp_f32_e32 v179, v83
	v_exp_f32_e32 v100, v100
	v_exp_f32_e32 v101, v101
	v_exp_f32_e32 v180, v84
	v_exp_f32_e32 v181, v85
	v_exp_f32_e32 v102, v102
	v_exp_f32_e32 v103, v103
	v_exp_f32_e32 v182, v86
	v_exp_f32_e32 v183, v87
	v_exp_f32_e32 v104, v104
	v_exp_f32_e32 v105, v105
	v_exp_f32_e32 v184, v88
	v_exp_f32_e32 v185, v89
	v_exp_f32_e32 v106, v106
	v_exp_f32_e32 v107, v107
	v_exp_f32_e32 v186, v90
	v_exp_f32_e32 v187, v91
	v_exp_f32_e32 v108, v108
	v_exp_f32_e32 v109, v109
	v_exp_f32_e32 v188, v92
	v_exp_f32_e32 v189, v93
	v_exp_f32_e32 v110, v110
	v_exp_f32_e32 v111, v111
	v_exp_f32_e32 v190, v94
	v_exp_f32_e32 v191, v95
	v_cvt_pk_bf16_f32 v80, v96, v97
	v_cvt_pk_bf16_f32 v81, v98, v99
	v_cvt_pk_bf16_f32 v82, v100, v101
	v_cvt_pk_bf16_f32 v83, v102, v103
	v_cvt_pk_bf16_f32 v84, v104, v105
	v_cvt_pk_bf16_f32 v85, v106, v107
	v_cvt_pk_bf16_f32 v86, v108, v109
	v_cvt_pk_bf16_f32 v87, v110, v111
	v_cvt_pk_bf16_f32 v88, v176, v177
	v_cvt_pk_bf16_f32 v89, v178, v179
	v_cvt_pk_bf16_f32 v90, v180, v181
	v_cvt_pk_bf16_f32 v91, v182, v183
	v_cvt_pk_bf16_f32 v92, v184, v185
	v_cvt_pk_bf16_f32 v93, v186, v187
	v_cvt_pk_bf16_f32 v94, v188, v189
	v_cvt_pk_bf16_f32 v95, v190, v191
	v_pk_add_f32 v[96:97], v[96:97], v[100:101]
	v_pk_add_f32 v[98:99], v[98:99], v[102:103]
	v_pk_add_f32 v[176:177], v[176:177], v[180:181]
	v_pk_add_f32 v[178:179], v[178:179], v[182:183]
	v_pk_add_f32 v[96:97], v[96:97], v[104:105]
	v_pk_add_f32 v[98:99], v[98:99], v[106:107]
	v_pk_add_f32 v[176:177], v[176:177], v[184:185]
	v_pk_add_f32 v[178:179], v[178:179], v[186:187]
	v_pk_add_f32 v[96:97], v[96:97], v[108:109]
	v_pk_add_f32 v[98:99], v[98:99], v[110:111]
	v_pk_add_f32 v[176:177], v[176:177], v[188:189]
	v_pk_add_f32 v[178:179], v[178:179], v[190:191]
	v_pk_add_f32 v[136:137], v[136:137], v[96:97]
	v_pk_add_f32 v[138:139], v[138:139], v[98:99]
	v_pk_add_f32 v[140:141], v[140:141], v[176:177]
	v_pk_add_f32 v[142:143], v[142:143], v[178:179]
	v_add_u32_e32 v205, 0x5000, v165
	v_add_u32_e32 v206, 0x20400, v192
	s_waitcnt vmcnt(5) lgkmcnt(0)
	s_barrier
	s_setprio 1
	ds_read_b64_tr_b16 v[96:97], v205 offset:34816
	ds_read_b64_tr_b16 v[98:99], v205 offset:37376
	ds_read_b64_tr_b16 v[100:101], v205 offset:39936
	ds_read_b64_tr_b16 v[102:103], v205 offset:42496
	ds_read_b64_tr_b16 v[104:105], v205 offset:45056
	ds_read_b64_tr_b16 v[106:107], v205 offset:47616
	ds_read_b64_tr_b16 v[108:109], v205 offset:50176
	ds_read_b64_tr_b16 v[110:111], v205 offset:52736
	ds_read_b64_tr_b16 v[176:177], v205 offset:34880
	ds_read_b64_tr_b16 v[178:179], v205 offset:37440
	ds_read_b64_tr_b16 v[180:181], v205 offset:40000
	ds_read_b64_tr_b16 v[182:183], v205 offset:42560
	ds_read_b64_tr_b16 v[184:185], v205 offset:45120
	ds_read_b64_tr_b16 v[186:187], v205 offset:47680
	s_waitcnt lgkmcnt(12)
	v_mfma_f32_32x32x16_bf16 v[32:47], v[96:99], v[80:83], v[32:47]
	ds_read_b64_tr_b16 v[96:97], v205 offset:50240
	ds_read_b64_tr_b16 v[98:99], v205 offset:52800
	s_waitcnt lgkmcnt(12)
	v_mfma_f32_32x32x16_bf16 v[32:47], v[100:103], v[84:87], v[32:47]
	ds_read_b64_tr_b16 v[100:101], v205 offset:34944
	ds_read_b64_tr_b16 v[102:103], v205 offset:37504
	s_waitcnt lgkmcnt(12)
	v_mfma_f32_32x32x16_bf16 v[32:47], v[104:107], v[88:91], v[32:47]
	ds_read_b64_tr_b16 v[104:105], v205 offset:40064
	ds_read_b64_tr_b16 v[106:107], v205 offset:42624
	s_waitcnt lgkmcnt(12)
	v_mfma_f32_32x32x16_bf16 v[32:47], v[108:111], v[92:95], v[32:47]
	ds_read_b64_tr_b16 v[108:109], v205 offset:45184
	ds_read_b64_tr_b16 v[110:111], v205 offset:47744
	s_waitcnt lgkmcnt(12)
	v_mfma_f32_32x32x16_bf16 v[16:31], v[176:179], v[80:83], v[16:31]
	ds_read_b64_tr_b16 v[176:177], v205 offset:50304
	ds_read_b64_tr_b16 v[178:179], v205 offset:52864
	s_waitcnt lgkmcnt(12)
	v_mfma_f32_32x32x16_bf16 v[16:31], v[180:183], v[84:87], v[16:31]
	ds_read_b64_tr_b16 v[180:181], v205 offset:35008
	ds_read_b64_tr_b16 v[182:183], v205 offset:37568
	s_waitcnt lgkmcnt(12)
	v_mfma_f32_32x32x16_bf16 v[16:31], v[184:187], v[88:91], v[16:31]
	ds_read_b64_tr_b16 v[184:185], v205 offset:40128
	ds_read_b64_tr_b16 v[186:187], v205 offset:42688
	s_waitcnt lgkmcnt(12)
	v_mfma_f32_32x32x16_bf16 v[16:31], v[96:99], v[92:95], v[16:31]
	ds_read_b64_tr_b16 v[96:97], v205 offset:45248
	ds_read_b64_tr_b16 v[98:99], v205 offset:47808
	s_waitcnt lgkmcnt(12)
	v_mfma_f32_32x32x16_bf16 v[0:15], v[100:103], v[80:83], v[0:15]
	ds_read_b64_tr_b16 v[100:101], v205 offset:50368
	ds_read_b64_tr_b16 v[102:103], v205 offset:52928
	s_waitcnt lgkmcnt(12)
	v_mfma_f32_32x32x16_bf16 v[0:15], v[104:107], v[84:87], v[0:15]
	ds_read_b128 v[210:213], v206 offset:8704
	ds_read_b128 v[104:107], v206 offset:8736
	s_waitcnt lgkmcnt(12)
	v_mfma_f32_32x32x16_bf16 v[0:15], v[108:111], v[88:91], v[0:15]
	ds_read_b128 v[108:111], v206 offset:8768
	ds_read_b128 v[188:191], v206
	s_waitcnt lgkmcnt(12)
	v_mfma_f32_32x32x16_bf16 v[0:15], v[176:179], v[92:95], v[0:15]
	ds_read_b128 v[176:179], v206 offset:8800
	ds_read_b128 v[224:227], v206 offset:32
	s_waitcnt lgkmcnt(12)
	v_mfma_f32_32x32x16_bf16 v[48:63], v[180:183], v[80:83], v[48:63]
	ds_read_b128 v[228:231], v206 offset:64
	ds_read_b128 v[248:251], v206 offset:96
	s_waitcnt lgkmcnt(12)
	v_mfma_f32_32x32x16_bf16 v[48:63], v[184:187], v[84:87], v[48:63]
	s_waitcnt lgkmcnt(10)
	v_mfma_f32_32x32x16_bf16 v[48:63], v[96:99], v[88:91], v[48:63]
	s_waitcnt lgkmcnt(8)
	v_mfma_f32_32x32x16_bf16 v[48:63], v[100:103], v[92:95], v[48:63]
	s_waitcnt lgkmcnt(7)
	v_mfma_f32_32x32x16_bf16 v[80:95], v[210:213], v[112:115], v[64:79]
	s_waitcnt lgkmcnt(6)
	v_mfma_f32_32x32x16_bf16 v[80:95], v[104:107], v[116:119], v[80:95]
	s_waitcnt lgkmcnt(5)
	v_mfma_f32_32x32x16_bf16 v[80:95], v[108:111], v[120:123], v[80:95]
	s_waitcnt lgkmcnt(3)
	v_mfma_f32_32x32x16_bf16 v[80:95], v[176:179], v[124:127], v[80:95]
	s_waitcnt lgkmcnt(4)
	v_mfma_f32_32x32x16_bf16 v[96:111], v[188:191], v[112:115], v[64:79]
	s_waitcnt lgkmcnt(2)
	v_mfma_f32_32x32x16_bf16 v[96:111], v[224:227], v[116:119], v[96:111]
	s_waitcnt lgkmcnt(1)
	v_mfma_f32_32x32x16_bf16 v[96:111], v[228:231], v[120:123], v[96:111]
	s_waitcnt lgkmcnt(0)
	v_mfma_f32_32x32x16_bf16 v[96:111], v[248:251], v[124:127], v[96:111]
	s_setprio 0
	s_add_i32 s65, s65, 1
	s_add_i32 s33, s33, -1
.LBF2_top:
	s_cmp_ge_i32 s65, s69
	s_cbranch_scc1 .LB2_top
	s_add_i32 m0, s32, 0x4400
	s_add_u32 s80, s80, 0x20000
	s_addc_u32 s81, s81, 0
	global_load_lds_dwordx4 v128, s[80:81]
	s_add_i32 m0, m0, 0x2000
	s_nop 0
	global_load_lds_dwordx4 v129, s[80:81]
	s_add_i32 m0, s32, 0x8800
	s_nop 0
	global_load_lds_dwordx4 v130, s[80:81]
	s_add_i32 m0, m0, 0x2000
	s_nop 0
	global_load_lds_dwordx4 v131, s[80:81]
	s_mov_b32 m0, s28
	s_nop 0
	global_load_lds_dwordx4 v132, s[80:81]
	v_max_f32_e32 v176, v96, v80
	v_max3_f32 v177, v81, v98, v82
	v_max3_f32 v176, v176, v97, v99
	v_max3_f32 v177, v177, v100, v84
	v_max3_f32 v176, v176, v83, v101
	v_max3_f32 v177, v177, v102, v86
	v_max3_f32 v176, v176, v85, v103
	v_max3_f32 v177, v177, v104, v88
	v_max3_f32 v176, v176, v87, v105
	v_max3_f32 v177, v177, v106, v90
	v_max3_f32 v176, v176, v89, v107
	v_max3_f32 v177, v177, v108, v92
	v_max3_f32 v176, v176, v91, v109
	v_max3_f32 v177, v177, v110, v94
	v_max3_f32 v176, v176, v93, v111
	v_max3_f32 v176, v176, v95, v177
	v_cmp_lt_f32_e32 vcc, 0x41000000, v176
	s_cbranch_vccnz .Lrs_bf2
.Latt_bf2_exp:
	v_exp_f32_e32 v96, v96
	v_exp_f32_e32 v97, v97
	v_exp_f32_e32 v176, v80
	v_exp_f32_e32 v177, v81
	v_exp_f32_e32 v98, v98
	v_exp_f32_e32 v99, v99
	v_exp_f32_e32 v178, v82
	v_exp_f32_e32 v179, v83
	v_exp_f32_e32 v100, v100
	v_exp_f32_e32 v101, v101
	v_exp_f32_e32 v180, v84
	v_exp_f32_e32 v181, v85
	v_exp_f32_e32 v102, v102
	v_exp_f32_e32 v103, v103
	v_exp_f32_e32 v182, v86
	v_exp_f32_e32 v183, v87
	v_exp_f32_e32 v104, v104
	v_exp_f32_e32 v105, v105
	v_exp_f32_e32 v184, v88
	v_exp_f32_e32 v185, v89
	v_exp_f32_e32 v106, v106
	v_exp_f32_e32 v107, v107
	v_exp_f32_e32 v186, v90
	v_exp_f32_e32 v187, v91
	v_exp_f32_e32 v108, v108
	v_exp_f32_e32 v109, v109
	v_exp_f32_e32 v188, v92
	v_exp_f32_e32 v189, v93
	v_exp_f32_e32 v110, v110
	v_exp_f32_e32 v111, v111
	v_exp_f32_e32 v190, v94
	v_exp_f32_e32 v191, v95
	v_cvt_pk_bf16_f32 v80, v96, v97
	v_cvt_pk_bf16_f32 v81, v98, v99
	v_cvt_pk_bf16_f32 v82, v100, v101
	v_cvt_pk_bf16_f32 v83, v102, v103
	v_cvt_pk_bf16_f32 v84, v104, v105
	v_cvt_pk_bf16_f32 v85, v106, v107
	v_cvt_pk_bf16_f32 v86, v108, v109
	v_cvt_pk_bf16_f32 v87, v110, v111
	v_cvt_pk_bf16_f32 v88, v176, v177
	v_cvt_pk_bf16_f32 v89, v178, v179
	v_cvt_pk_bf16_f32 v90, v180, v181
	v_cvt_pk_bf16_f32 v91, v182, v183
	v_cvt_pk_bf16_f32 v92, v184, v185
	v_cvt_pk_bf16_f32 v93, v186, v187
	v_cvt_pk_bf16_f32 v94, v188, v189
	v_cvt_pk_bf16_f32 v95, v190, v191
	v_pk_add_f32 v[96:97], v[96:97], v[100:101]
	v_pk_add_f32 v[98:99], v[98:99], v[102:103]
	v_pk_add_f32 v[176:177], v[176:177], v[180:181]
	v_pk_add_f32 v[178:179], v[178:179], v[182:183]
	v_pk_add_f32 v[96:97], v[96:97], v[104:105]
	v_pk_add_f32 v[98:99], v[98:99], v[106:107]
	v_pk_add_f32 v[176:177], v[176:177], v[184:185]
	v_pk_add_f32 v[178:179], v[178:179], v[186:187]
	v_pk_add_f32 v[96:97], v[96:97], v[108:109]
	v_pk_add_f32 v[98:99], v[98:99], v[110:111]
	v_pk_add_f32 v[176:177], v[176:177], v[188:189]
	v_pk_add_f32 v[178:179], v[178:179], v[190:191]
	v_pk_add_f32 v[136:137], v[136:137], v[96:97]
	v_pk_add_f32 v[138:139], v[138:139], v[98:99]
	v_pk_add_f32 v[140:141], v[140:141], v[176:177]
	v_pk_add_f32 v[142:143], v[142:143], v[178:179]
	v_add_u32_e32 v205, 0xa000, v165
	v_add_u32_e32 v206, 0x0, v192
	s_waitcnt vmcnt(5) lgkmcnt(0)
	s_barrier
	s_setprio 1
	ds_read_b64_tr_b16 v[96:97], v205 offset:34816
	ds_read_b64_tr_b16 v[98:99], v205 offset:37376
	ds_read_b64_tr_b16 v[100:101], v205 offset:39936
	ds_read_b64_tr_b16 v[102:103], v205 offset:42496
	ds_read_b64_tr_b16 v[104:105], v205 offset:45056
	ds_read_b64_tr_b16 v[106:107], v205 offset:47616
	ds_read_b64_tr_b16 v[108:109], v205 offset:50176
	ds_read_b64_tr_b16 v[110:111], v205 offset:52736
	ds_read_b64_tr_b16 v[176:177], v205 offset:34880
	ds_read_b64_tr_b16 v[178:179], v205 offset:37440
	ds_read_b64_tr_b16 v[180:181], v205 offset:40000
	ds_read_b64_tr_b16 v[182:183], v205 offset:42560
	ds_read_b64_tr_b16 v[184:185], v205 offset:45120
	ds_read_b64_tr_b16 v[186:187], v205 offset:47680
	s_waitcnt lgkmcnt(12)
	v_mfma_f32_32x32x16_bf16 v[32:47], v[96:99], v[80:83], v[32:47]
	ds_read_b64_tr_b16 v[96:97], v205 offset:50240
	ds_read_b64_tr_b16 v[98:99], v205 offset:52800
	s_waitcnt lgkmcnt(12)
	v_mfma_f32_32x32x16_bf16 v[32:47], v[100:103], v[84:87], v[32:47]
	ds_read_b64_tr_b16 v[100:101], v205 offset:34944
	ds_read_b64_tr_b16 v[102:103], v205 offset:37504
	s_waitcnt lgkmcnt(12)
	v_mfma_f32_32x32x16_bf16 v[32:47], v[104:107], v[88:91], v[32:47]
	ds_read_b64_tr_b16 v[104:105], v205 offset:40064
	ds_read_b64_tr_b16 v[106:107], v205 offset:42624
	s_waitcnt lgkmcnt(12)
	v_mfma_f32_32x32x16_bf16 v[32:47], v[108:111], v[92:95], v[32:47]
	ds_read_b64_tr_b16 v[108:109], v205 offset:45184
	ds_read_b64_tr_b16 v[110:111], v205 offset:47744
	s_waitcnt lgkmcnt(12)
	v_mfma_f32_32x32x16_bf16 v[16:31], v[176:179], v[80:83], v[16:31]
	ds_read_b64_tr_b16 v[176:177], v205 offset:50304
	ds_read_b64_tr_b16 v[178:179], v205 offset:52864
	s_waitcnt lgkmcnt(12)
	v_mfma_f32_32x32x16_bf16 v[16:31], v[180:183], v[84:87], v[16:31]
	ds_read_b64_tr_b16 v[180:181], v205 offset:35008
	ds_read_b64_tr_b16 v[182:183], v205 offset:37568
	s_waitcnt lgkmcnt(12)
	v_mfma_f32_32x32x16_bf16 v[16:31], v[184:187], v[88:91], v[16:31]
	ds_read_b64_tr_b16 v[184:185], v205 offset:40128
	ds_read_b64_tr_b16 v[186:187], v205 offset:42688
	s_waitcnt lgkmcnt(12)
	v_mfma_f32_32x32x16_bf16 v[16:31], v[96:99], v[92:95], v[16:31]
	ds_read_b64_tr_b16 v[96:97], v205 offset:45248
	ds_read_b64_tr_b16 v[98:99], v205 offset:47808
	s_waitcnt lgkmcnt(12)
	v_mfma_f32_32x32x16_bf16 v[0:15], v[100:103], v[80:83], v[0:15]
	ds_read_b64_tr_b16 v[100:101], v205 offset:50368
	ds_read_b64_tr_b16 v[102:103], v205 offset:52928
	s_waitcnt lgkmcnt(12)
	v_mfma_f32_32x32x16_bf16 v[0:15], v[104:107], v[84:87], v[0:15]
	ds_read_b128 v[210:213], v206 offset:8704
	ds_read_b128 v[104:107], v206 offset:8736
	s_waitcnt lgkmcnt(12)
	v_mfma_f32_32x32x16_bf16 v[0:15], v[108:111], v[88:91], v[0:15]
	ds_read_b128 v[108:111], v206 offset:8768
	ds_read_b128 v[188:191], v206
	s_waitcnt lgkmcnt(12)
	v_mfma_f32_32x32x16_bf16 v[0:15], v[176:179], v[92:95], v[0:15]
	ds_read_b128 v[176:179], v206 offset:8800
	ds_read_b128 v[224:227], v206 offset:32
	s_waitcnt lgkmcnt(12)
	v_mfma_f32_32x32x16_bf16 v[48:63], v[180:183], v[80:83], v[48:63]
	ds_read_b128 v[228:231], v206 offset:64
	ds_read_b128 v[248:251], v206 offset:96
	s_waitcnt lgkmcnt(12)
	v_mfma_f32_32x32x16_bf16 v[48:63], v[184:187], v[84:87], v[48:63]
	s_waitcnt lgkmcnt(10)
	v_mfma_f32_32x32x16_bf16 v[48:63], v[96:99], v[88:91], v[48:63]
	s_waitcnt lgkmcnt(8)
	v_mfma_f32_32x32x16_bf16 v[48:63], v[100:103], v[92:95], v[48:63]
	s_waitcnt lgkmcnt(7)
	v_mfma_f32_32x32x16_bf16 v[80:95], v[210:213], v[112:115], v[64:79]
	s_waitcnt lgkmcnt(6)
	v_mfma_f32_32x32x16_bf16 v[80:95], v[104:107], v[116:119], v[80:95]
	s_waitcnt lgkmcnt(5)
	v_mfma_f32_32x32x16_bf16 v[80:95], v[108:111], v[120:123], v[80:95]
	s_waitcnt lgkmcnt(3)
	v_mfma_f32_32x32x16_bf16 v[80:95], v[176:179], v[124:127], v[80:95]
	s_waitcnt lgkmcnt(4)
	v_mfma_f32_32x32x16_bf16 v[96:111], v[188:191], v[112:115], v[64:79]
	s_waitcnt lgkmcnt(2)
	v_mfma_f32_32x32x16_bf16 v[96:111], v[224:227], v[116:119], v[96:111]
	s_waitcnt lgkmcnt(1)
	v_mfma_f32_32x32x16_bf16 v[96:111], v[228:231], v[120:123], v[96:111]
	s_waitcnt lgkmcnt(0)
	v_mfma_f32_32x32x16_bf16 v[96:111], v[248:251], v[124:127], v[96:111]
	s_setprio 0
	s_add_i32 s65, s65, 1
	s_add_i32 s33, s33, -1
.LBF0_top:
	s_cmp_ge_i32 s65, s69
	s_cbranch_scc1 .LB0_top
	s_add_i32 m0, s32, 0x20400
	s_add_u32 s80, s80, 0x20000
	s_addc_u32 s81, s81, 0
	global_load_lds_dwordx4 v128, s[80:81]
	s_add_i32 m0, m0, 0x2000
	s_nop 0
	global_load_lds_dwordx4 v129, s[80:81]
	s_add_i32 m0, s32, 0xd800
	s_nop 0
	global_load_lds_dwordx4 v130, s[80:81]
	s_add_i32 m0, m0, 0x2000
	s_nop 0
	global_load_lds_dwordx4 v131, s[80:81]
	s_mov_b32 m0, s29
	s_nop 0
	global_load_lds_dwordx4 v132, s[80:81]
	v_max_f32_e32 v176, v96, v80
	v_max3_f32 v177, v81, v98, v82
	v_max3_f32 v176, v176, v97, v99
	v_max3_f32 v177, v177, v100, v84
	v_max3_f32 v176, v176, v83, v101
	v_max3_f32 v177, v177, v102, v86
	v_max3_f32 v176, v176, v85, v103
	v_max3_f32 v177, v177, v104, v88
	v_max3_f32 v176, v176, v87, v105
	v_max3_f32 v177, v177, v106, v90
	v_max3_f32 v176, v176, v89, v107
	v_max3_f32 v177, v177, v108, v92
	v_max3_f32 v176, v176, v91, v109
	v_max3_f32 v177, v177, v110, v94
	v_max3_f32 v176, v176, v93, v111
	v_max3_f32 v176, v176, v95, v177
	v_cmp_lt_f32_e32 vcc, 0x41000000, v176
	s_cbranch_vccnz .Lrs_bf0
.Latt_bf0_exp:
	v_exp_f32_e32 v96, v96
	v_exp_f32_e32 v97, v97
	v_exp_f32_e32 v176, v80
	v_exp_f32_e32 v177, v81
	v_exp_f32_e32 v98, v98
	v_exp_f32_e32 v99, v99
	v_exp_f32_e32 v178, v82
	v_exp_f32_e32 v179, v83
	v_exp_f32_e32 v100, v100
	v_exp_f32_e32 v101, v101
	v_exp_f32_e32 v180, v84
	v_exp_f32_e32 v181, v85
	v_exp_f32_e32 v102, v102
	v_exp_f32_e32 v103, v103
	v_exp_f32_e32 v182, v86
	v_exp_f32_e32 v183, v87
	v_exp_f32_e32 v104, v104
	v_exp_f32_e32 v105, v105
	v_exp_f32_e32 v184, v88
	v_exp_f32_e32 v185, v89
	v_exp_f32_e32 v106, v106
	v_exp_f32_e32 v107, v107
	v_exp_f32_e32 v186, v90
	v_exp_f32_e32 v187, v91
	v_exp_f32_e32 v108, v108
	v_exp_f32_e32 v109, v109
	v_exp_f32_e32 v188, v92
	v_exp_f32_e32 v189, v93
	v_exp_f32_e32 v110, v110
	v_exp_f32_e32 v111, v111
	v_exp_f32_e32 v190, v94
	v_exp_f32_e32 v191, v95
	v_cvt_pk_bf16_f32 v80, v96, v97
	v_cvt_pk_bf16_f32 v81, v98, v99
	v_cvt_pk_bf16_f32 v82, v100, v101
	v_cvt_pk_bf16_f32 v83, v102, v103
	v_cvt_pk_bf16_f32 v84, v104, v105
	v_cvt_pk_bf16_f32 v85, v106, v107
	v_cvt_pk_bf16_f32 v86, v108, v109
	v_cvt_pk_bf16_f32 v87, v110, v111
	v_cvt_pk_bf16_f32 v88, v176, v177
	v_cvt_pk_bf16_f32 v89, v178, v179
	v_cvt_pk_bf16_f32 v90, v180, v181
	v_cvt_pk_bf16_f32 v91, v182, v183
	v_cvt_pk_bf16_f32 v92, v184, v185
	v_cvt_pk_bf16_f32 v93, v186, v187
	v_cvt_pk_bf16_f32 v94, v188, v189
	v_cvt_pk_bf16_f32 v95, v190, v191
	v_pk_add_f32 v[96:97], v[96:97], v[100:101]
	v_pk_add_f32 v[98:99], v[98:99], v[102:103]
	v_pk_add_f32 v[176:177], v[176:177], v[180:181]
	v_pk_add_f32 v[178:179], v[178:179], v[182:183]
	v_pk_add_f32 v[96:97], v[96:97], v[104:105]
	v_pk_add_f32 v[98:99], v[98:99], v[106:107]
	v_pk_add_f32 v[176:177], v[176:177], v[184:185]
	v_pk_add_f32 v[178:179], v[178:179], v[186:187]
	v_pk_add_f32 v[96:97], v[96:97], v[108:109]
	v_pk_add_f32 v[98:99], v[98:99], v[110:111]
	v_pk_add_f32 v[176:177], v[176:177], v[188:189]
	v_pk_add_f32 v[178:179], v[178:179], v[190:191]
	v_pk_add_f32 v[136:137], v[136:137], v[96:97]
	v_pk_add_f32 v[138:139], v[138:139], v[98:99]
	v_pk_add_f32 v[140:141], v[140:141], v[176:177]
	v_pk_add_f32 v[142:143], v[142:143], v[178:179]
	v_add_u32_e32 v205, 0x0, v165
	v_add_u32_e32 v206, 0x4400, v192
	s_waitcnt vmcnt(5) lgkmcnt(0)
	s_barrier
	s_setprio 1
	ds_read_b64_tr_b16 v[96:97], v205 offset:34816
	ds_read_b64_tr_b16 v[98:99], v205 offset:37376
	ds_read_b64_tr_b16 v[100:101], v205 offset:39936
	ds_read_b64_tr_b16 v[102:103], v205 offset:42496
	ds_read_b64_tr_b16 v[104:105], v205 offset:45056
	ds_read_b64_tr_b16 v[106:107], v205 offset:47616
	ds_read_b64_tr_b16 v[108:109], v205 offset:50176
	ds_read_b64_tr_b16 v[110:111], v205 offset:52736
	ds_read_b64_tr_b16 v[176:177], v205 offset:34880
	ds_read_b64_tr_b16 v[178:179], v205 offset:37440
	ds_read_b64_tr_b16 v[180:181], v205 offset:40000
	ds_read_b64_tr_b16 v[182:183], v205 offset:42560
	ds_read_b64_tr_b16 v[184:185], v205 offset:45120
	ds_read_b64_tr_b16 v[186:187], v205 offset:47680
	s_waitcnt lgkmcnt(12)
	v_mfma_f32_32x32x16_bf16 v[32:47], v[96:99], v[80:83], v[32:47]
	ds_read_b64_tr_b16 v[96:97], v205 offset:50240
	ds_read_b64_tr_b16 v[98:99], v205 offset:52800
	s_waitcnt lgkmcnt(12)
	v_mfma_f32_32x32x16_bf16 v[32:47], v[100:103], v[84:87], v[32:47]
	ds_read_b64_tr_b16 v[100:101], v205 offset:34944
	ds_read_b64_tr_b16 v[102:103], v205 offset:37504
	s_waitcnt lgkmcnt(12)
	v_mfma_f32_32x32x16_bf16 v[32:47], v[104:107], v[88:91], v[32:47]
	ds_read_b64_tr_b16 v[104:105], v205 offset:40064
	ds_read_b64_tr_b16 v[106:107], v205 offset:42624
	s_waitcnt lgkmcnt(12)
	v_mfma_f32_32x32x16_bf16 v[32:47], v[108:111], v[92:95], v[32:47]
	ds_read_b64_tr_b16 v[108:109], v205 offset:45184
	ds_read_b64_tr_b16 v[110:111], v205 offset:47744
	s_waitcnt lgkmcnt(12)
	v_mfma_f32_32x32x16_bf16 v[16:31], v[176:179], v[80:83], v[16:31]
	ds_read_b64_tr_b16 v[176:177], v205 offset:50304
	ds_read_b64_tr_b16 v[178:179], v205 offset:52864
	s_waitcnt lgkmcnt(12)
	v_mfma_f32_32x32x16_bf16 v[16:31], v[180:183], v[84:87], v[16:31]
	ds_read_b64_tr_b16 v[180:181], v205 offset:35008
	ds_read_b64_tr_b16 v[182:183], v205 offset:37568
	s_waitcnt lgkmcnt(12)
	v_mfma_f32_32x32x16_bf16 v[16:31], v[184:187], v[88:91], v[16:31]
	ds_read_b64_tr_b16 v[184:185], v205 offset:40128
	ds_read_b64_tr_b16 v[186:187], v205 offset:42688
	s_waitcnt lgkmcnt(12)
	v_mfma_f32_32x32x16_bf16 v[16:31], v[96:99], v[92:95], v[16:31]
	ds_read_b64_tr_b16 v[96:97], v205 offset:45248
	ds_read_b64_tr_b16 v[98:99], v205 offset:47808
	s_waitcnt lgkmcnt(12)
	v_mfma_f32_32x32x16_bf16 v[0:15], v[100:103], v[80:83], v[0:15]
	ds_read_b64_tr_b16 v[100:101], v205 offset:50368
	ds_read_b64_tr_b16 v[102:103], v205 offset:52928
	s_waitcnt lgkmcnt(12)
	v_mfma_f32_32x32x16_bf16 v[0:15], v[104:107], v[84:87], v[0:15]
	ds_read_b128 v[210:213], v206 offset:8704
	ds_read_b128 v[104:107], v206 offset:8736
	s_waitcnt lgkmcnt(12)
	v_mfma_f32_32x32x16_bf16 v[0:15], v[108:111], v[88:91], v[0:15]
	ds_read_b128 v[108:111], v206 offset:8768
	ds_read_b128 v[188:191], v206
	s_waitcnt lgkmcnt(12)
	v_mfma_f32_32x32x16_bf16 v[0:15], v[176:179], v[92:95], v[0:15]
	ds_read_b128 v[176:179], v206 offset:8800
	ds_read_b128 v[224:227], v206 offset:32
	s_waitcnt lgkmcnt(12)
	v_mfma_f32_32x32x16_bf16 v[48:63], v[180:183], v[80:83], v[48:63]
	ds_read_b128 v[228:231], v206 offset:64
	ds_read_b128 v[248:251], v206 offset:96
	s_waitcnt lgkmcnt(12)
	v_mfma_f32_32x32x16_bf16 v[48:63], v[184:187], v[84:87], v[48:63]
	s_waitcnt lgkmcnt(10)
	v_mfma_f32_32x32x16_bf16 v[48:63], v[96:99], v[88:91], v[48:63]
	s_waitcnt lgkmcnt(8)
	v_mfma_f32_32x32x16_bf16 v[48:63], v[100:103], v[92:95], v[48:63]
	s_waitcnt lgkmcnt(7)
	v_mfma_f32_32x32x16_bf16 v[80:95], v[210:213], v[112:115], v[64:79]
	s_waitcnt lgkmcnt(6)
	v_mfma_f32_32x32x16_bf16 v[80:95], v[104:107], v[116:119], v[80:95]
	s_waitcnt lgkmcnt(5)
	v_mfma_f32_32x32x16_bf16 v[80:95], v[108:111], v[120:123], v[80:95]
	s_waitcnt lgkmcnt(3)
	v_mfma_f32_32x32x16_bf16 v[80:95], v[176:179], v[124:127], v[80:95]
	s_waitcnt lgkmcnt(4)
	v_mfma_f32_32x32x16_bf16 v[96:111], v[188:191], v[112:115], v[64:79]
	s_waitcnt lgkmcnt(2)
	v_mfma_f32_32x32x16_bf16 v[96:111], v[224:227], v[116:119], v[96:111]
	s_waitcnt lgkmcnt(1)
	v_mfma_f32_32x32x16_bf16 v[96:111], v[228:231], v[120:123], v[96:111]
	s_waitcnt lgkmcnt(0)
	v_mfma_f32_32x32x16_bf16 v[96:111], v[248:251], v[124:127], v[96:111]
	s_setprio 0
	s_add_i32 s65, s65, 1
	s_add_i32 s33, s33, -1
	s_branch .LBF1_top

.LAF1_top:
	s_cmp_ge_i32 s65, s69
	s_cbranch_scc1 .LA1_top
	s_setprio 1
	v_add_u32_e32 v205, 0x0, v165
	v_add_u32_e32 v206, 0x4400, v192
	ds_read_b64_tr_b16 v[96:97], v205 offset:34816
	ds_read_b64_tr_b16 v[98:99], v205 offset:37376
	ds_read_b64_tr_b16 v[100:101], v205 offset:39936
	ds_read_b64_tr_b16 v[102:103], v205 offset:42496
	ds_read_b64_tr_b16 v[104:105], v205 offset:45056
	ds_read_b64_tr_b16 v[106:107], v205 offset:47616
	ds_read_b64_tr_b16 v[108:109], v205 offset:50176
	ds_read_b64_tr_b16 v[110:111], v205 offset:52736
	ds_read_b64_tr_b16 v[176:177], v205 offset:34880
	ds_read_b64_tr_b16 v[178:179], v205 offset:37440
	ds_read_b64_tr_b16 v[180:181], v205 offset:40000
	ds_read_b64_tr_b16 v[182:183], v205 offset:42560
	ds_read_b64_tr_b16 v[184:185], v205 offset:45120
	ds_read_b64_tr_b16 v[186:187], v205 offset:47680
	s_waitcnt lgkmcnt(12)
	v_mfma_f32_32x32x16_bf16 v[32:47], v[96:99], v[80:83], v[32:47]
	ds_read_b64_tr_b16 v[96:97], v205 offset:50240
	ds_read_b64_tr_b16 v[98:99], v205 offset:52800
	s_waitcnt lgkmcnt(12)
	v_mfma_f32_32x32x16_bf16 v[32:47], v[100:103], v[84:87], v[32:47]
	ds_read_b64_tr_b16 v[100:101], v205 offset:34944
	ds_read_b64_tr_b16 v[102:103], v205 offset:37504
	s_waitcnt lgkmcnt(12)
	v_mfma_f32_32x32x16_bf16 v[32:47], v[104:107], v[88:91], v[32:47]
	ds_read_b64_tr_b16 v[104:105], v205 offset:40064
	ds_read_b64_tr_b16 v[106:107], v205 offset:42624
	s_waitcnt lgkmcnt(12)
	v_mfma_f32_32x32x16_bf16 v[32:47], v[108:111], v[92:95], v[32:47]
	ds_read_b64_tr_b16 v[108:109], v205 offset:45184
	ds_read_b64_tr_b16 v[110:111], v205 offset:47744
	s_waitcnt lgkmcnt(12)
	v_mfma_f32_32x32x16_bf16 v[16:31], v[176:179], v[80:83], v[16:31]
	ds_read_b64_tr_b16 v[176:177], v205 offset:50304
	ds_read_b64_tr_b16 v[178:179], v205 offset:52864
	s_waitcnt lgkmcnt(12)
	v_mfma_f32_32x32x16_bf16 v[16:31], v[180:183], v[84:87], v[16:31]
	ds_read_b64_tr_b16 v[180:181], v205 offset:35008
	ds_read_b64_tr_b16 v[182:183], v205 offset:37568
	s_waitcnt lgkmcnt(12)
	v_mfma_f32_32x32x16_bf16 v[16:31], v[184:187], v[88:91], v[16:31]
	ds_read_b64_tr_b16 v[184:185], v205 offset:40128
	ds_read_b64_tr_b16 v[186:187], v205 offset:42688
	s_waitcnt lgkmcnt(12)
	v_mfma_f32_32x32x16_bf16 v[16:31], v[96:99], v[92:95], v[16:31]
	ds_read_b64_tr_b16 v[96:97], v205 offset:45248
	ds_read_b64_tr_b16 v[98:99], v205 offset:47808
	s_waitcnt lgkmcnt(12)
	v_mfma_f32_32x32x16_bf16 v[0:15], v[100:103], v[80:83], v[0:15]
	ds_read_b64_tr_b16 v[100:101], v205 offset:50368
	ds_read_b64_tr_b16 v[102:103], v205 offset:52928
	s_waitcnt lgkmcnt(12)
	v_mfma_f32_32x32x16_bf16 v[0:15], v[104:107], v[84:87], v[0:15]
	ds_read_b128 v[210:213], v206 offset:8704
	ds_read_b128 v[104:107], v206 offset:8736
	s_waitcnt lgkmcnt(12)
	v_mfma_f32_32x32x16_bf16 v[0:15], v[108:111], v[88:91], v[0:15]
	ds_read_b128 v[108:111], v206 offset:8768
	ds_read_b128 v[188:191], v206
	s_waitcnt lgkmcnt(12)
	v_mfma_f32_32x32x16_bf16 v[0:15], v[176:179], v[92:95], v[0:15]
	ds_read_b128 v[176:179], v206 offset:8800
	ds_read_b128 v[224:227], v206 offset:32
	s_waitcnt lgkmcnt(12)
	v_mfma_f32_32x32x16_bf16 v[48:63], v[180:183], v[80:83], v[48:63]
	ds_read_b128 v[228:231], v206 offset:64
	ds_read_b128 v[248:251], v206 offset:96
	s_waitcnt lgkmcnt(12)
	v_mfma_f32_32x32x16_bf16 v[48:63], v[184:187], v[84:87], v[48:63]
	s_waitcnt lgkmcnt(10)
	v_mfma_f32_32x32x16_bf16 v[48:63], v[96:99], v[88:91], v[48:63]
	s_waitcnt lgkmcnt(8)
	v_mfma_f32_32x32x16_bf16 v[48:63], v[100:103], v[92:95], v[48:63]
	s_waitcnt lgkmcnt(7)
	v_mfma_f32_32x32x16_bf16 v[80:95], v[210:213], v[112:115], v[64:79]
	s_waitcnt lgkmcnt(6)
	v_mfma_f32_32x32x16_bf16 v[80:95], v[104:107], v[116:119], v[80:95]
	s_waitcnt lgkmcnt(5)
	v_mfma_f32_32x32x16_bf16 v[80:95], v[108:111], v[120:123], v[80:95]
	s_waitcnt lgkmcnt(3)
	v_mfma_f32_32x32x16_bf16 v[80:95], v[176:179], v[124:127], v[80:95]
	s_waitcnt lgkmcnt(4)
	v_mfma_f32_32x32x16_bf16 v[96:111], v[188:191], v[112:115], v[64:79]
	s_waitcnt lgkmcnt(2)
	v_mfma_f32_32x32x16_bf16 v[96:111], v[224:227], v[116:119], v[96:111]
	s_waitcnt lgkmcnt(1)
	v_mfma_f32_32x32x16_bf16 v[96:111], v[228:231], v[120:123], v[96:111]
	s_waitcnt lgkmcnt(0)
	v_mfma_f32_32x32x16_bf16 v[96:111], v[248:251], v[124:127], v[96:111]
	s_setprio 0
	s_cmp_eq_u32 s56, 4
	s_cbranch_scc1 .Lw5_af1
	s_waitcnt vmcnt(4) lgkmcnt(0)

.Latt_af1_exp:
	v_exp_f32_e32 v96, v96
	v_exp_f32_e32 v97, v97
	v_exp_f32_e32 v176, v80
	v_exp_f32_e32 v177, v81
	v_exp_f32_e32 v98, v98
	v_exp_f32_e32 v99, v99
	v_exp_f32_e32 v178, v82
	v_exp_f32_e32 v179, v83
	v_exp_f32_e32 v100, v100
	v_exp_f32_e32 v101, v101
	v_exp_f32_e32 v180, v84
	v_exp_f32_e32 v181, v85
	v_exp_f32_e32 v102, v102
	v_exp_f32_e32 v103, v103
	v_exp_f32_e32 v182, v86
	v_exp_f32_e32 v183, v87
	v_exp_f32_e32 v104, v104
	v_exp_f32_e32 v105, v105
	v_exp_f32_e32 v184, v88
	v_exp_f32_e32 v185, v89
	v_exp_f32_e32 v106, v106
	v_exp_f32_e32 v107, v107
	v_exp_f32_e32 v186, v90
	v_exp_f32_e32 v187, v91
	v_exp_f32_e32 v108, v108
	v_exp_f32_e32 v109, v109
	v_exp_f32_e32 v188, v92
	v_exp_f32_e32 v189, v93
	v_exp_f32_e32 v110, v110
	v_exp_f32_e32 v111, v111
	v_exp_f32_e32 v190, v94
	v_exp_f32_e32 v191, v95
	v_cvt_pk_bf16_f32 v80, v96, v97
	v_cvt_pk_bf16_f32 v81, v98, v99
	v_cvt_pk_bf16_f32 v82, v100, v101
	v_cvt_pk_bf16_f32 v83, v102, v103
	v_cvt_pk_bf16_f32 v84, v104, v105
	v_cvt_pk_bf16_f32 v85, v106, v107
	v_cvt_pk_bf16_f32 v86, v108, v109
	v_cvt_pk_bf16_f32 v87, v110, v111
	v_cvt_pk_bf16_f32 v88, v176, v177
	v_cvt_pk_bf16_f32 v89, v178, v179
	v_cvt_pk_bf16_f32 v90, v180, v181
	v_cvt_pk_bf16_f32 v91, v182, v183
	v_cvt_pk_bf16_f32 v92, v184, v185
	v_cvt_pk_bf16_f32 v93, v186, v187
	v_cvt_pk_bf16_f32 v94, v188, v189
	v_cvt_pk_bf16_f32 v95, v190, v191
	v_pk_add_f32 v[96:97], v[96:97], v[100:101]
	v_pk_add_f32 v[98:99], v[98:99], v[102:103]
	v_pk_add_f32 v[176:177], v[176:177], v[180:181]
	v_pk_add_f32 v[178:179], v[178:179], v[182:183]
	v_pk_add_f32 v[96:97], v[96:97], v[104:105]
	v_pk_add_f32 v[98:99], v[98:99], v[106:107]
	v_pk_add_f32 v[176:177], v[176:177], v[184:185]
	v_pk_add_f32 v[178:179], v[178:179], v[186:187]
	v_pk_add_f32 v[96:97], v[96:97], v[108:109]
	v_pk_add_f32 v[98:99], v[98:99], v[110:111]
	v_pk_add_f32 v[176:177], v[176:177], v[188:189]
	v_pk_add_f32 v[178:179], v[178:179], v[190:191]
	v_pk_add_f32 v[136:137], v[136:137], v[96:97]
	v_pk_add_f32 v[138:139], v[138:139], v[98:99]
	v_pk_add_f32 v[140:141], v[140:141], v[176:177]
	v_pk_add_f32 v[142:143], v[142:143], v[178:179]
	s_add_i32 s65, s65, 1
	s_add_i32 s33, s33, -1
.LAF2_top:
	s_cmp_ge_i32 s65, s69
	s_cbranch_scc1 .LA2_top
	s_setprio 1
	v_add_u32_e32 v205, 0x5000, v165
	v_add_u32_e32 v206, 0x20400, v192
	ds_read_b64_tr_b16 v[96:97], v205 offset:34816
	ds_read_b64_tr_b16 v[98:99], v205 offset:37376
	ds_read_b64_tr_b16 v[100:101], v205 offset:39936
	ds_read_b64_tr_b16 v[102:103], v205 offset:42496
	ds_read_b64_tr_b16 v[104:105], v205 offset:45056
	ds_read_b64_tr_b16 v[106:107], v205 offset:47616
	ds_read_b64_tr_b16 v[108:109], v205 offset:50176
	ds_read_b64_tr_b16 v[110:111], v205 offset:52736
	ds_read_b64_tr_b16 v[176:177], v205 offset:34880
	ds_read_b64_tr_b16 v[178:179], v205 offset:37440
	ds_read_b64_tr_b16 v[180:181], v205 offset:40000
	ds_read_b64_tr_b16 v[182:183], v205 offset:42560
	ds_read_b64_tr_b16 v[184:185], v205 offset:45120
	ds_read_b64_tr_b16 v[186:187], v205 offset:47680
	s_waitcnt lgkmcnt(12)
	v_mfma_f32_32x32x16_bf16 v[32:47], v[96:99], v[80:83], v[32:47]
	ds_read_b64_tr_b16 v[96:97], v205 offset:50240
	ds_read_b64_tr_b16 v[98:99], v205 offset:52800
	s_waitcnt lgkmcnt(12)
	v_mfma_f32_32x32x16_bf16 v[32:47], v[100:103], v[84:87], v[32:47]
	ds_read_b64_tr_b16 v[100:101], v205 offset:34944
	ds_read_b64_tr_b16 v[102:103], v205 offset:37504
	s_waitcnt lgkmcnt(12)
	v_mfma_f32_32x32x16_bf16 v[32:47], v[104:107], v[88:91], v[32:47]
	ds_read_b64_tr_b16 v[104:105], v205 offset:40064
	ds_read_b64_tr_b16 v[106:107], v205 offset:42624
	s_waitcnt lgkmcnt(12)
	v_mfma_f32_32x32x16_bf16 v[32:47], v[108:111], v[92:95], v[32:47]
	ds_read_b64_tr_b16 v[108:109], v205 offset:45184
	ds_read_b64_tr_b16 v[110:111], v205 offset:47744
	s_waitcnt lgkmcnt(12)
	v_mfma_f32_32x32x16_bf16 v[16:31], v[176:179], v[80:83], v[16:31]
	ds_read_b64_tr_b16 v[176:177], v205 offset:50304
	ds_read_b64_tr_b16 v[178:179], v205 offset:52864
	s_waitcnt lgkmcnt(12)
	v_mfma_f32_32x32x16_bf16 v[16:31], v[180:183], v[84:87], v[16:31]
	ds_read_b64_tr_b16 v[180:181], v205 offset:35008
	ds_read_b64_tr_b16 v[182:183], v205 offset:37568
	s_waitcnt lgkmcnt(12)
	v_mfma_f32_32x32x16_bf16 v[16:31], v[184:187], v[88:91], v[16:31]
	ds_read_b64_tr_b16 v[184:185], v205 offset:40128
	ds_read_b64_tr_b16 v[186:187], v205 offset:42688
	s_waitcnt lgkmcnt(12)
	v_mfma_f32_32x32x16_bf16 v[16:31], v[96:99], v[92:95], v[16:31]
	ds_read_b64_tr_b16 v[96:97], v205 offset:45248
	ds_read_b64_tr_b16 v[98:99], v205 offset:47808
	s_waitcnt lgkmcnt(12)
	v_mfma_f32_32x32x16_bf16 v[0:15], v[100:103], v[80:83], v[0:15]
	ds_read_b64_tr_b16 v[100:101], v205 offset:50368
	ds_read_b64_tr_b16 v[102:103], v205 offset:52928
	s_waitcnt lgkmcnt(12)
	v_mfma_f32_32x32x16_bf16 v[0:15], v[104:107], v[84:87], v[0:15]
	ds_read_b128 v[210:213], v206 offset:8704
	ds_read_b128 v[104:107], v206 offset:8736
	s_waitcnt lgkmcnt(12)
	v_mfma_f32_32x32x16_bf16 v[0:15], v[108:111], v[88:91], v[0:15]
	ds_read_b128 v[108:111], v206 offset:8768
	ds_read_b128 v[188:191], v206
	s_waitcnt lgkmcnt(12)
	v_mfma_f32_32x32x16_bf16 v[0:15], v[176:179], v[92:95], v[0:15]
	ds_read_b128 v[176:179], v206 offset:8800
	ds_read_b128 v[224:227], v206 offset:32
	s_waitcnt lgkmcnt(12)
	v_mfma_f32_32x32x16_bf16 v[48:63], v[180:183], v[80:83], v[48:63]
	ds_read_b128 v[228:231], v206 offset:64
	ds_read_b128 v[248:251], v206 offset:96
	s_waitcnt lgkmcnt(12)
	v_mfma_f32_32x32x16_bf16 v[48:63], v[184:187], v[84:87], v[48:63]
	s_waitcnt lgkmcnt(10)
	v_mfma_f32_32x32x16_bf16 v[48:63], v[96:99], v[88:91], v[48:63]
	s_waitcnt lgkmcnt(8)
	v_mfma_f32_32x32x16_bf16 v[48:63], v[100:103], v[92:95], v[48:63]
	s_waitcnt lgkmcnt(7)
	v_mfma_f32_32x32x16_bf16 v[80:95], v[210:213], v[112:115], v[64:79]
	s_waitcnt lgkmcnt(6)
	v_mfma_f32_32x32x16_bf16 v[80:95], v[104:107], v[116:119], v[80:95]
	s_waitcnt lgkmcnt(5)
	v_mfma_f32_32x32x16_bf16 v[80:95], v[108:111], v[120:123], v[80:95]
	s_waitcnt lgkmcnt(3)
	v_mfma_f32_32x32x16_bf16 v[80:95], v[176:179], v[124:127], v[80:95]
	s_waitcnt lgkmcnt(4)
	v_mfma_f32_32x32x16_bf16 v[96:111], v[188:191], v[112:115], v[64:79]
	s_waitcnt lgkmcnt(2)
	v_mfma_f32_32x32x16_bf16 v[96:111], v[224:227], v[116:119], v[96:111]
	s_waitcnt lgkmcnt(1)
	v_mfma_f32_32x32x16_bf16 v[96:111], v[228:231], v[120:123], v[96:111]
	s_waitcnt lgkmcnt(0)
	v_mfma_f32_32x32x16_bf16 v[96:111], v[248:251], v[124:127], v[96:111]
	s_setprio 0
	s_cmp_eq_u32 s56, 4
	s_cbranch_scc1 .Lw5_af2
	s_waitcnt vmcnt(4) lgkmcnt(0)

.LAF0_top:
	s_cmp_ge_i32 s65, s69
	s_cbranch_scc1 .LA0_top
	s_setprio 1
	v_add_u32_e32 v205, 0xa000, v165
	v_add_u32_e32 v206, 0x0, v192
	ds_read_b64_tr_b16 v[96:97], v205 offset:34816
	ds_read_b64_tr_b16 v[98:99], v205 offset:37376
	ds_read_b64_tr_b16 v[100:101], v205 offset:39936
	ds_read_b64_tr_b16 v[102:103], v205 offset:42496
	ds_read_b64_tr_b16 v[104:105], v205 offset:45056
	ds_read_b64_tr_b16 v[106:107], v205 offset:47616
	ds_read_b64_tr_b16 v[108:109], v205 offset:50176
	ds_read_b64_tr_b16 v[110:111], v205 offset:52736
	ds_read_b64_tr_b16 v[176:177], v205 offset:34880
	ds_read_b64_tr_b16 v[178:179], v205 offset:37440
	ds_read_b64_tr_b16 v[180:181], v205 offset:40000
	ds_read_b64_tr_b16 v[182:183], v205 offset:42560
	ds_read_b64_tr_b16 v[184:185], v205 offset:45120
	ds_read_b64_tr_b16 v[186:187], v205 offset:47680
	s_waitcnt lgkmcnt(12)
	v_mfma_f32_32x32x16_bf16 v[32:47], v[96:99], v[80:83], v[32:47]
	ds_read_b64_tr_b16 v[96:97], v205 offset:50240
	ds_read_b64_tr_b16 v[98:99], v205 offset:52800
	s_waitcnt lgkmcnt(12)
	v_mfma_f32_32x32x16_bf16 v[32:47], v[100:103], v[84:87], v[32:47]
	ds_read_b64_tr_b16 v[100:101], v205 offset:34944
	ds_read_b64_tr_b16 v[102:103], v205 offset:37504
	s_waitcnt lgkmcnt(12)
	v_mfma_f32_32x32x16_bf16 v[32:47], v[104:107], v[88:91], v[32:47]
	ds_read_b64_tr_b16 v[104:105], v205 offset:40064
	ds_read_b64_tr_b16 v[106:107], v205 offset:42624
	s_waitcnt lgkmcnt(12)
	v_mfma_f32_32x32x16_bf16 v[32:47], v[108:111], v[92:95], v[32:47]
	ds_read_b64_tr_b16 v[108:109], v205 offset:45184
	ds_read_b64_tr_b16 v[110:111], v205 offset:47744
	s_waitcnt lgkmcnt(12)
	v_mfma_f32_32x32x16_bf16 v[16:31], v[176:179], v[80:83], v[16:31]
	ds_read_b64_tr_b16 v[176:177], v205 offset:50304
	ds_read_b64_tr_b16 v[178:179], v205 offset:52864
	s_waitcnt lgkmcnt(12)
	v_mfma_f32_32x32x16_bf16 v[16:31], v[180:183], v[84:87], v[16:31]
	ds_read_b64_tr_b16 v[180:181], v205 offset:35008
	ds_read_b64_tr_b16 v[182:183], v205 offset:37568
	s_waitcnt lgkmcnt(12)
	v_mfma_f32_32x32x16_bf16 v[16:31], v[184:187], v[88:91], v[16:31]
	ds_read_b64_tr_b16 v[184:185], v205 offset:40128
	ds_read_b64_tr_b16 v[186:187], v205 offset:42688
	s_waitcnt lgkmcnt(12)
	v_mfma_f32_32x32x16_bf16 v[16:31], v[96:99], v[92:95], v[16:31]
	ds_read_b64_tr_b16 v[96:97], v205 offset:45248
	ds_read_b64_tr_b16 v[98:99], v205 offset:47808
	s_waitcnt lgkmcnt(12)
	v_mfma_f32_32x32x16_bf16 v[0:15], v[100:103], v[80:83], v[0:15]
	ds_read_b64_tr_b16 v[100:101], v205 offset:50368
	ds_read_b64_tr_b16 v[102:103], v205 offset:52928
	s_waitcnt lgkmcnt(12)
	v_mfma_f32_32x32x16_bf16 v[0:15], v[104:107], v[84:87], v[0:15]
	ds_read_b128 v[210:213], v206 offset:8704
	ds_read_b128 v[104:107], v206 offset:8736
	s_waitcnt lgkmcnt(12)
	v_mfma_f32_32x32x16_bf16 v[0:15], v[108:111], v[88:91], v[0:15]
	ds_read_b128 v[108:111], v206 offset:8768
	ds_read_b128 v[188:191], v206
	s_waitcnt lgkmcnt(12)
	v_mfma_f32_32x32x16_bf16 v[0:15], v[176:179], v[92:95], v[0:15]
	ds_read_b128 v[176:179], v206 offset:8800
	ds_read_b128 v[224:227], v206 offset:32
	s_waitcnt lgkmcnt(12)
	v_mfma_f32_32x32x16_bf16 v[48:63], v[180:183], v[80:83], v[48:63]
	ds_read_b128 v[228:231], v206 offset:64
	ds_read_b128 v[248:251], v206 offset:96
	s_waitcnt lgkmcnt(12)
	v_mfma_f32_32x32x16_bf16 v[48:63], v[184:187], v[84:87], v[48:63]
	s_waitcnt lgkmcnt(10)
	v_mfma_f32_32x32x16_bf16 v[48:63], v[96:99], v[88:91], v[48:63]
	s_waitcnt lgkmcnt(8)
	v_mfma_f32_32x32x16_bf16 v[48:63], v[100:103], v[92:95], v[48:63]
	s_waitcnt lgkmcnt(7)
	v_mfma_f32_32x32x16_bf16 v[80:95], v[210:213], v[112:115], v[64:79]
	s_waitcnt lgkmcnt(6)
	v_mfma_f32_32x32x16_bf16 v[80:95], v[104:107], v[116:119], v[80:95]
	s_waitcnt lgkmcnt(5)
	v_mfma_f32_32x32x16_bf16 v[80:95], v[108:111], v[120:123], v[80:95]
	s_waitcnt lgkmcnt(3)
	v_mfma_f32_32x32x16_bf16 v[80:95], v[176:179], v[124:127], v[80:95]
	s_waitcnt lgkmcnt(4)
	v_mfma_f32_32x32x16_bf16 v[96:111], v[188:191], v[112:115], v[64:79]
	s_waitcnt lgkmcnt(2)
	v_mfma_f32_32x32x16_bf16 v[96:111], v[224:227], v[116:119], v[96:111]
	s_waitcnt lgkmcnt(1)
	v_mfma_f32_32x32x16_bf16 v[96:111], v[228:231], v[120:123], v[96:111]
	s_waitcnt lgkmcnt(0)
	v_mfma_f32_32x32x16_bf16 v[96:111], v[248:251], v[124:127], v[96:111]
	s_setprio 0
	s_cmp_eq_u32 s56, 4
	s_cbranch_scc1 .Lw5_af0
	s_waitcnt vmcnt(4) lgkmcnt(0)

.Latt_af0_exp:
	v_exp_f32_e32 v96, v96
	v_exp_f32_e32 v97, v97
	v_exp_f32_e32 v176, v80
	v_exp_f32_e32 v177, v81
	v_exp_f32_e32 v98, v98
	v_exp_f32_e32 v99, v99
	v_exp_f32_e32 v178, v82
	v_exp_f32_e32 v179, v83
	v_exp_f32_e32 v100, v100
	v_exp_f32_e32 v101, v101
	v_exp_f32_e32 v180, v84
	v_exp_f32_e32 v181, v85
	v_exp_f32_e32 v102, v102
	v_exp_f32_e32 v103, v103
	v_exp_f32_e32 v182, v86
	v_exp_f32_e32 v183, v87
	v_exp_f32_e32 v104, v104
	v_exp_f32_e32 v105, v105
	v_exp_f32_e32 v184, v88
	v_exp_f32_e32 v185, v89
	v_exp_f32_e32 v106, v106
	v_exp_f32_e32 v107, v107
	v_exp_f32_e32 v186, v90
	v_exp_f32_e32 v187, v91
	v_exp_f32_e32 v108, v108
	v_exp_f32_e32 v109, v109
	v_exp_f32_e32 v188, v92
	v_exp_f32_e32 v189, v93
	v_exp_f32_e32 v110, v110
	v_exp_f32_e32 v111, v111
	v_exp_f32_e32 v190, v94
	v_exp_f32_e32 v191, v95
	v_cvt_pk_bf16_f32 v80, v96, v97
	v_cvt_pk_bf16_f32 v81, v98, v99
	v_cvt_pk_bf16_f32 v82, v100, v101
	v_cvt_pk_bf16_f32 v83, v102, v103
	v_cvt_pk_bf16_f32 v84, v104, v105
	v_cvt_pk_bf16_f32 v85, v106, v107
	v_cvt_pk_bf16_f32 v86, v108, v109
	v_cvt_pk_bf16_f32 v87, v110, v111
	v_cvt_pk_bf16_f32 v88, v176, v177
	v_cvt_pk_bf16_f32 v89, v178, v179
	v_cvt_pk_bf16_f32 v90, v180, v181
	v_cvt_pk_bf16_f32 v91, v182, v183
	v_cvt_pk_bf16_f32 v92, v184, v185
	v_cvt_pk_bf16_f32 v93, v186, v187
	v_cvt_pk_bf16_f32 v94, v188, v189
	v_cvt_pk_bf16_f32 v95, v190, v191
	v_pk_add_f32 v[96:97], v[96:97], v[100:101]
	v_pk_add_f32 v[98:99], v[98:99], v[102:103]
	v_pk_add_f32 v[176:177], v[176:177], v[180:181]
	v_pk_add_f32 v[178:179], v[178:179], v[182:183]
	v_pk_add_f32 v[96:97], v[96:97], v[104:105]
	v_pk_add_f32 v[98:99], v[98:99], v[106:107]
	v_pk_add_f32 v[176:177], v[176:177], v[184:185]
	v_pk_add_f32 v[178:179], v[178:179], v[186:187]
	v_pk_add_f32 v[96:97], v[96:97], v[108:109]
	v_pk_add_f32 v[98:99], v[98:99], v[110:111]
	v_pk_add_f32 v[176:177], v[176:177], v[188:189]
	v_pk_add_f32 v[178:179], v[178:179], v[190:191]
	v_pk_add_f32 v[136:137], v[136:137], v[96:97]
	v_pk_add_f32 v[138:139], v[138:139], v[98:99]
	v_pk_add_f32 v[140:141], v[140:141], v[176:177]
	v_pk_add_f32 v[142:143], v[142:143], v[178:179]
	s_add_i32 s65, s65, 1
	s_add_i32 s33, s33, -1
	s_branch .LAF1_top

.LA0_end:
	s_add_i32 s65, s65, 1
	s_add_i32 s33, s33, -1
	s_cmp_gt_u32 s65, s66
	s_cbranch_scc1 .LA0_exit
	s_branch .LA1_top
.Lrs_bf1:
	v_mov_b32_e32 v177, v176
	s_nop 1
	v_permlane32_swap_b32_e32 v176, v177
	v_max_f32_e32 v176, v176, v177
	v_max_f32_e32 v64, v176, v176
	v_max_f32_e32 v66, 0, v64
	v_exp_f32_e64 v176, -v66
	v_add_f32_e32 v173, v173, v66
	v_xor_b32_e32 v64, 0x80000000, v173
	v_pk_add_f32 v[96:97], v[96:97], v[66:67] op_sel_hi:[1,0] neg_lo:[0,1] neg_hi:[0,1]
	v_pk_add_f32 v[80:81], v[80:81], v[66:67] op_sel_hi:[1,0] neg_lo:[0,1] neg_hi:[0,1]
	v_pk_add_f32 v[98:99], v[98:99], v[66:67] op_sel_hi:[1,0] neg_lo:[0,1] neg_hi:[0,1]
	v_pk_add_f32 v[82:83], v[82:83], v[66:67] op_sel_hi:[1,0] neg_lo:[0,1] neg_hi:[0,1]
	v_pk_add_f32 v[100:101], v[100:101], v[66:67] op_sel_hi:[1,0] neg_lo:[0,1] neg_hi:[0,1]
	v_pk_add_f32 v[84:85], v[84:85], v[66:67] op_sel_hi:[1,0] neg_lo:[0,1] neg_hi:[0,1]
	v_pk_add_f32 v[102:103], v[102:103], v[66:67] op_sel_hi:[1,0] neg_lo:[0,1] neg_hi:[0,1]
	v_pk_add_f32 v[86:87], v[86:87], v[66:67] op_sel_hi:[1,0] neg_lo:[0,1] neg_hi:[0,1]
	v_pk_add_f32 v[104:105], v[104:105], v[66:67] op_sel_hi:[1,0] neg_lo:[0,1] neg_hi:[0,1]
	v_pk_add_f32 v[88:89], v[88:89], v[66:67] op_sel_hi:[1,0] neg_lo:[0,1] neg_hi:[0,1]
	v_pk_add_f32 v[106:107], v[106:107], v[66:67] op_sel_hi:[1,0] neg_lo:[0,1] neg_hi:[0,1]
	v_pk_add_f32 v[90:91], v[90:91], v[66:67] op_sel_hi:[1,0] neg_lo:[0,1] neg_hi:[0,1]
	v_pk_add_f32 v[108:109], v[108:109], v[66:67] op_sel_hi:[1,0] neg_lo:[0,1] neg_hi:[0,1]
	v_pk_add_f32 v[92:93], v[92:93], v[66:67] op_sel_hi:[1,0] neg_lo:[0,1] neg_hi:[0,1]
	v_pk_add_f32 v[110:111], v[110:111], v[66:67] op_sel_hi:[1,0] neg_lo:[0,1] neg_hi:[0,1]
	v_pk_add_f32 v[94:95], v[94:95], v[66:67] op_sel_hi:[1,0] neg_lo:[0,1] neg_hi:[0,1]
	v_mov_b32_e32 v65, v64
	v_mov_b32_e32 v66, v64
	v_mov_b32_e32 v67, v64
	v_mov_b32_e32 v68, v64
	v_mov_b32_e32 v69, v64
	v_mov_b32_e32 v70, v64
	v_mov_b32_e32 v71, v64
	v_mov_b32_e32 v72, v64
	v_mov_b32_e32 v73, v64
	v_mov_b32_e32 v74, v64
	v_mov_b32_e32 v75, v64
	v_mov_b32_e32 v76, v64
	v_mov_b32_e32 v77, v64
	v_mov_b32_e32 v78, v64
	v_mov_b32_e32 v79, v64
	v_pk_mul_f32 v[46:47], v[46:47], v[176:177] op_sel_hi:[1,0]
	v_pk_mul_f32 v[44:45], v[44:45], v[176:177] op_sel_hi:[1,0]
	v_pk_mul_f32 v[42:43], v[42:43], v[176:177] op_sel_hi:[1,0]
	v_pk_mul_f32 v[40:41], v[40:41], v[176:177] op_sel_hi:[1,0]
	v_pk_mul_f32 v[38:39], v[38:39], v[176:177] op_sel_hi:[1,0]
	v_pk_mul_f32 v[36:37], v[36:37], v[176:177] op_sel_hi:[1,0]
	v_pk_mul_f32 v[34:35], v[34:35], v[176:177] op_sel_hi:[1,0]
	v_pk_mul_f32 v[32:33], v[32:33], v[176:177] op_sel_hi:[1,0]
	v_pk_mul_f32 v[30:31], v[30:31], v[176:177] op_sel_hi:[1,0]
	v_pk_mul_f32 v[28:29], v[28:29], v[176:177] op_sel_hi:[1,0]
	v_pk_mul_f32 v[26:27], v[26:27], v[176:177] op_sel_hi:[1,0]
	v_pk_mul_f32 v[24:25], v[24:25], v[176:177] op_sel_hi:[1,0]
	v_pk_mul_f32 v[22:23], v[22:23], v[176:177] op_sel_hi:[1,0]
	v_pk_mul_f32 v[20:21], v[20:21], v[176:177] op_sel_hi:[1,0]
	v_pk_mul_f32 v[18:19], v[18:19], v[176:177] op_sel_hi:[1,0]
	v_pk_mul_f32 v[16:17], v[16:17], v[176:177] op_sel_hi:[1,0]
	v_pk_mul_f32 v[14:15], v[14:15], v[176:177] op_sel_hi:[1,0]
	v_pk_mul_f32 v[12:13], v[12:13], v[176:177] op_sel_hi:[1,0]
	v_pk_mul_f32 v[10:11], v[10:11], v[176:177] op_sel_hi:[1,0]
	v_pk_mul_f32 v[8:9], v[8:9], v[176:177] op_sel_hi:[1,0]
	v_pk_mul_f32 v[6:7], v[6:7], v[176:177] op_sel_hi:[1,0]
	v_pk_mul_f32 v[4:5], v[4:5], v[176:177] op_sel_hi:[1,0]
	v_pk_mul_f32 v[2:3], v[2:3], v[176:177] op_sel_hi:[1,0]
	v_pk_mul_f32 v[0:1], v[0:1], v[176:177] op_sel_hi:[1,0]
	v_pk_mul_f32 v[62:63], v[62:63], v[176:177] op_sel_hi:[1,0]
	v_pk_mul_f32 v[60:61], v[60:61], v[176:177] op_sel_hi:[1,0]
	v_pk_mul_f32 v[58:59], v[58:59], v[176:177] op_sel_hi:[1,0]
	v_pk_mul_f32 v[56:57], v[56:57], v[176:177] op_sel_hi:[1,0]
	v_pk_mul_f32 v[54:55], v[54:55], v[176:177] op_sel_hi:[1,0]
	v_pk_mul_f32 v[52:53], v[52:53], v[176:177] op_sel_hi:[1,0]
	v_pk_mul_f32 v[50:51], v[50:51], v[176:177] op_sel_hi:[1,0]
	v_pk_mul_f32 v[48:49], v[48:49], v[176:177] op_sel_hi:[1,0]
	v_mul_f32_e32 v172, v172, v176
	v_pk_mul_f32 v[136:137], v[136:137], v[176:177] op_sel_hi:[1,0]
	v_pk_mul_f32 v[138:139], v[138:139], v[176:177] op_sel_hi:[1,0]
	v_pk_mul_f32 v[140:141], v[140:141], v[176:177] op_sel_hi:[1,0]
	v_pk_mul_f32 v[142:143], v[142:143], v[176:177] op_sel_hi:[1,0]
	s_branch .Latt_bf1_exp
.Lrs_bf2:
	v_mov_b32_e32 v177, v176
	s_nop 1
	v_permlane32_swap_b32_e32 v176, v177
	v_max_f32_e32 v176, v176, v177
	v_max_f32_e32 v64, v176, v176
	v_max_f32_e32 v66, 0, v64
	v_exp_f32_e64 v176, -v66
	v_add_f32_e32 v173, v173, v66
	v_xor_b32_e32 v64, 0x80000000, v173
	v_pk_add_f32 v[96:97], v[96:97], v[66:67] op_sel_hi:[1,0] neg_lo:[0,1] neg_hi:[0,1]
	v_pk_add_f32 v[80:81], v[80:81], v[66:67] op_sel_hi:[1,0] neg_lo:[0,1] neg_hi:[0,1]
	v_pk_add_f32 v[98:99], v[98:99], v[66:67] op_sel_hi:[1,0] neg_lo:[0,1] neg_hi:[0,1]
	v_pk_add_f32 v[82:83], v[82:83], v[66:67] op_sel_hi:[1,0] neg_lo:[0,1] neg_hi:[0,1]
	v_pk_add_f32 v[100:101], v[100:101], v[66:67] op_sel_hi:[1,0] neg_lo:[0,1] neg_hi:[0,1]
	v_pk_add_f32 v[84:85], v[84:85], v[66:67] op_sel_hi:[1,0] neg_lo:[0,1] neg_hi:[0,1]
	v_pk_add_f32 v[102:103], v[102:103], v[66:67] op_sel_hi:[1,0] neg_lo:[0,1] neg_hi:[0,1]
	v_pk_add_f32 v[86:87], v[86:87], v[66:67] op_sel_hi:[1,0] neg_lo:[0,1] neg_hi:[0,1]
	v_pk_add_f32 v[104:105], v[104:105], v[66:67] op_sel_hi:[1,0] neg_lo:[0,1] neg_hi:[0,1]
	v_pk_add_f32 v[88:89], v[88:89], v[66:67] op_sel_hi:[1,0] neg_lo:[0,1] neg_hi:[0,1]
	v_pk_add_f32 v[106:107], v[106:107], v[66:67] op_sel_hi:[1,0] neg_lo:[0,1] neg_hi:[0,1]
	v_pk_add_f32 v[90:91], v[90:91], v[66:67] op_sel_hi:[1,0] neg_lo:[0,1] neg_hi:[0,1]
	v_pk_add_f32 v[108:109], v[108:109], v[66:67] op_sel_hi:[1,0] neg_lo:[0,1] neg_hi:[0,1]
	v_pk_add_f32 v[92:93], v[92:93], v[66:67] op_sel_hi:[1,0] neg_lo:[0,1] neg_hi:[0,1]
	v_pk_add_f32 v[110:111], v[110:111], v[66:67] op_sel_hi:[1,0] neg_lo:[0,1] neg_hi:[0,1]
	v_pk_add_f32 v[94:95], v[94:95], v[66:67] op_sel_hi:[1,0] neg_lo:[0,1] neg_hi:[0,1]
	v_mov_b32_e32 v65, v64
	v_mov_b32_e32 v66, v64
	v_mov_b32_e32 v67, v64
	v_mov_b32_e32 v68, v64
	v_mov_b32_e32 v69, v64
	v_mov_b32_e32 v70, v64
	v_mov_b32_e32 v71, v64
	v_mov_b32_e32 v72, v64
	v_mov_b32_e32 v73, v64
	v_mov_b32_e32 v74, v64
	v_mov_b32_e32 v75, v64
	v_mov_b32_e32 v76, v64
	v_mov_b32_e32 v77, v64
	v_mov_b32_e32 v78, v64
	v_mov_b32_e32 v79, v64
	v_pk_mul_f32 v[46:47], v[46:47], v[176:177] op_sel_hi:[1,0]
	v_pk_mul_f32 v[44:45], v[44:45], v[176:177] op_sel_hi:[1,0]
	v_pk_mul_f32 v[42:43], v[42:43], v[176:177] op_sel_hi:[1,0]
	v_pk_mul_f32 v[40:41], v[40:41], v[176:177] op_sel_hi:[1,0]
	v_pk_mul_f32 v[38:39], v[38:39], v[176:177] op_sel_hi:[1,0]
	v_pk_mul_f32 v[36:37], v[36:37], v[176:177] op_sel_hi:[1,0]
	v_pk_mul_f32 v[34:35], v[34:35], v[176:177] op_sel_hi:[1,0]
	v_pk_mul_f32 v[32:33], v[32:33], v[176:177] op_sel_hi:[1,0]
	v_pk_mul_f32 v[30:31], v[30:31], v[176:177] op_sel_hi:[1,0]
	v_pk_mul_f32 v[28:29], v[28:29], v[176:177] op_sel_hi:[1,0]
	v_pk_mul_f32 v[26:27], v[26:27], v[176:177] op_sel_hi:[1,0]
	v_pk_mul_f32 v[24:25], v[24:25], v[176:177] op_sel_hi:[1,0]
	v_pk_mul_f32 v[22:23], v[22:23], v[176:177] op_sel_hi:[1,0]
	v_pk_mul_f32 v[20:21], v[20:21], v[176:177] op_sel_hi:[1,0]
	v_pk_mul_f32 v[18:19], v[18:19], v[176:177] op_sel_hi:[1,0]
	v_pk_mul_f32 v[16:17], v[16:17], v[176:177] op_sel_hi:[1,0]
	v_pk_mul_f32 v[14:15], v[14:15], v[176:177] op_sel_hi:[1,0]
	v_pk_mul_f32 v[12:13], v[12:13], v[176:177] op_sel_hi:[1,0]
	v_pk_mul_f32 v[10:11], v[10:11], v[176:177] op_sel_hi:[1,0]
	v_pk_mul_f32 v[8:9], v[8:9], v[176:177] op_sel_hi:[1,0]
	v_pk_mul_f32 v[6:7], v[6:7], v[176:177] op_sel_hi:[1,0]
	v_pk_mul_f32 v[4:5], v[4:5], v[176:177] op_sel_hi:[1,0]
	v_pk_mul_f32 v[2:3], v[2:3], v[176:177] op_sel_hi:[1,0]
	v_pk_mul_f32 v[0:1], v[0:1], v[176:177] op_sel_hi:[1,0]
	v_pk_mul_f32 v[62:63], v[62:63], v[176:177] op_sel_hi:[1,0]
	v_pk_mul_f32 v[60:61], v[60:61], v[176:177] op_sel_hi:[1,0]
	v_pk_mul_f32 v[58:59], v[58:59], v[176:177] op_sel_hi:[1,0]
	v_pk_mul_f32 v[56:57], v[56:57], v[176:177] op_sel_hi:[1,0]
	v_pk_mul_f32 v[54:55], v[54:55], v[176:177] op_sel_hi:[1,0]
	v_pk_mul_f32 v[52:53], v[52:53], v[176:177] op_sel_hi:[1,0]
	v_pk_mul_f32 v[50:51], v[50:51], v[176:177] op_sel_hi:[1,0]
	v_pk_mul_f32 v[48:49], v[48:49], v[176:177] op_sel_hi:[1,0]
	v_mul_f32_e32 v172, v172, v176
	v_pk_mul_f32 v[136:137], v[136:137], v[176:177] op_sel_hi:[1,0]
	v_pk_mul_f32 v[138:139], v[138:139], v[176:177] op_sel_hi:[1,0]
	v_pk_mul_f32 v[140:141], v[140:141], v[176:177] op_sel_hi:[1,0]
	v_pk_mul_f32 v[142:143], v[142:143], v[176:177] op_sel_hi:[1,0]
	s_branch .Latt_bf2_exp
.Lrs_bf0:
	v_mov_b32_e32 v177, v176
	s_nop 1
	v_permlane32_swap_b32_e32 v176, v177
	v_max_f32_e32 v176, v176, v177
	v_max_f32_e32 v64, v176, v176
	v_max_f32_e32 v66, 0, v64
	v_exp_f32_e64 v176, -v66
	v_add_f32_e32 v173, v173, v66
	v_xor_b32_e32 v64, 0x80000000, v173
	v_pk_add_f32 v[96:97], v[96:97], v[66:67] op_sel_hi:[1,0] neg_lo:[0,1] neg_hi:[0,1]
	v_pk_add_f32 v[80:81], v[80:81], v[66:67] op_sel_hi:[1,0] neg_lo:[0,1] neg_hi:[0,1]
	v_pk_add_f32 v[98:99], v[98:99], v[66:67] op_sel_hi:[1,0] neg_lo:[0,1] neg_hi:[0,1]
	v_pk_add_f32 v[82:83], v[82:83], v[66:67] op_sel_hi:[1,0] neg_lo:[0,1] neg_hi:[0,1]
	v_pk_add_f32 v[100:101], v[100:101], v[66:67] op_sel_hi:[1,0] neg_lo:[0,1] neg_hi:[0,1]
	v_pk_add_f32 v[84:85], v[84:85], v[66:67] op_sel_hi:[1,0] neg_lo:[0,1] neg_hi:[0,1]
	v_pk_add_f32 v[102:103], v[102:103], v[66:67] op_sel_hi:[1,0] neg_lo:[0,1] neg_hi:[0,1]
	v_pk_add_f32 v[86:87], v[86:87], v[66:67] op_sel_hi:[1,0] neg_lo:[0,1] neg_hi:[0,1]
	v_pk_add_f32 v[104:105], v[104:105], v[66:67] op_sel_hi:[1,0] neg_lo:[0,1] neg_hi:[0,1]
	v_pk_add_f32 v[88:89], v[88:89], v[66:67] op_sel_hi:[1,0] neg_lo:[0,1] neg_hi:[0,1]
	v_pk_add_f32 v[106:107], v[106:107], v[66:67] op_sel_hi:[1,0] neg_lo:[0,1] neg_hi:[0,1]
	v_pk_add_f32 v[90:91], v[90:91], v[66:67] op_sel_hi:[1,0] neg_lo:[0,1] neg_hi:[0,1]
	v_pk_add_f32 v[108:109], v[108:109], v[66:67] op_sel_hi:[1,0] neg_lo:[0,1] neg_hi:[0,1]
	v_pk_add_f32 v[92:93], v[92:93], v[66:67] op_sel_hi:[1,0] neg_lo:[0,1] neg_hi:[0,1]
	v_pk_add_f32 v[110:111], v[110:111], v[66:67] op_sel_hi:[1,0] neg_lo:[0,1] neg_hi:[0,1]
	v_pk_add_f32 v[94:95], v[94:95], v[66:67] op_sel_hi:[1,0] neg_lo:[0,1] neg_hi:[0,1]
	v_mov_b32_e32 v65, v64
	v_mov_b32_e32 v66, v64
	v_mov_b32_e32 v67, v64
	v_mov_b32_e32 v68, v64
	v_mov_b32_e32 v69, v64
	v_mov_b32_e32 v70, v64
	v_mov_b32_e32 v71, v64
	v_mov_b32_e32 v72, v64
	v_mov_b32_e32 v73, v64
	v_mov_b32_e32 v74, v64
	v_mov_b32_e32 v75, v64
	v_mov_b32_e32 v76, v64
	v_mov_b32_e32 v77, v64
	v_mov_b32_e32 v78, v64
	v_mov_b32_e32 v79, v64
	v_pk_mul_f32 v[46:47], v[46:47], v[176:177] op_sel_hi:[1,0]
	v_pk_mul_f32 v[44:45], v[44:45], v[176:177] op_sel_hi:[1,0]
	v_pk_mul_f32 v[42:43], v[42:43], v[176:177] op_sel_hi:[1,0]
	v_pk_mul_f32 v[40:41], v[40:41], v[176:177] op_sel_hi:[1,0]
	v_pk_mul_f32 v[38:39], v[38:39], v[176:177] op_sel_hi:[1,0]
	v_pk_mul_f32 v[36:37], v[36:37], v[176:177] op_sel_hi:[1,0]
	v_pk_mul_f32 v[34:35], v[34:35], v[176:177] op_sel_hi:[1,0]
	v_pk_mul_f32 v[32:33], v[32:33], v[176:177] op_sel_hi:[1,0]
	v_pk_mul_f32 v[30:31], v[30:31], v[176:177] op_sel_hi:[1,0]
	v_pk_mul_f32 v[28:29], v[28:29], v[176:177] op_sel_hi:[1,0]
	v_pk_mul_f32 v[26:27], v[26:27], v[176:177] op_sel_hi:[1,0]
	v_pk_mul_f32 v[24:25], v[24:25], v[176:177] op_sel_hi:[1,0]
	v_pk_mul_f32 v[22:23], v[22:23], v[176:177] op_sel_hi:[1,0]
	v_pk_mul_f32 v[20:21], v[20:21], v[176:177] op_sel_hi:[1,0]
	v_pk_mul_f32 v[18:19], v[18:19], v[176:177] op_sel_hi:[1,0]
	v_pk_mul_f32 v[16:17], v[16:17], v[176:177] op_sel_hi:[1,0]
	v_pk_mul_f32 v[14:15], v[14:15], v[176:177] op_sel_hi:[1,0]
	v_pk_mul_f32 v[12:13], v[12:13], v[176:177] op_sel_hi:[1,0]
	v_pk_mul_f32 v[10:11], v[10:11], v[176:177] op_sel_hi:[1,0]
	v_pk_mul_f32 v[8:9], v[8:9], v[176:177] op_sel_hi:[1,0]
	v_pk_mul_f32 v[6:7], v[6:7], v[176:177] op_sel_hi:[1,0]
	v_pk_mul_f32 v[4:5], v[4:5], v[176:177] op_sel_hi:[1,0]
	v_pk_mul_f32 v[2:3], v[2:3], v[176:177] op_sel_hi:[1,0]
	v_pk_mul_f32 v[0:1], v[0:1], v[176:177] op_sel_hi:[1,0]
	v_pk_mul_f32 v[62:63], v[62:63], v[176:177] op_sel_hi:[1,0]
	v_pk_mul_f32 v[60:61], v[60:61], v[176:177] op_sel_hi:[1,0]
	v_pk_mul_f32 v[58:59], v[58:59], v[176:177] op_sel_hi:[1,0]
	v_pk_mul_f32 v[56:57], v[56:57], v[176:177] op_sel_hi:[1,0]
	v_pk_mul_f32 v[54:55], v[54:55], v[176:177] op_sel_hi:[1,0]
	v_pk_mul_f32 v[52:53], v[52:53], v[176:177] op_sel_hi:[1,0]
	v_pk_mul_f32 v[50:51], v[50:51], v[176:177] op_sel_hi:[1,0]
	v_pk_mul_f32 v[48:49], v[48:49], v[176:177] op_sel_hi:[1,0]
	v_mul_f32_e32 v172, v172, v176
	v_pk_mul_f32 v[136:137], v[136:137], v[176:177] op_sel_hi:[1,0]
	v_pk_mul_f32 v[138:139], v[138:139], v[176:177] op_sel_hi:[1,0]
	v_pk_mul_f32 v[140:141], v[140:141], v[176:177] op_sel_hi:[1,0]
	v_pk_mul_f32 v[142:143], v[142:143], v[176:177] op_sel_hi:[1,0]
	s_branch .Latt_bf0_exp
.Ltl_b1:
	s_cmp_ge_u32 s65, s66
	s_cbranch_scc1 .Ltl2_b1
	s_add_u32 s80, s80, 0x20000
	s_addc_u32 s81, s81, 0
	s_add_i32 m0, s32, 0x12800
	s_nop 0
	global_load_lds_dwordx4 v130, s[80:81]
	s_add_i32 m0, m0, 0x2000
	s_cmp_eq_u32 s56, 0
	global_load_lds_dwordx4 v131, s[80:81]
	s_cbranch_scc1 .Ltl2_b1
	s_mov_b32 m0, s5
	s_nop 0
	global_load_lds_dwordx4 v132, s[80:81]

.LB0_exit:
	s_mov_b32 s69, 0
	s_branch .LBB0_243
.Lrs_af1:
	v_mov_b32_e32 v177, v176
	s_nop 1
	v_permlane32_swap_b32_e32 v176, v177
	v_max_f32_e32 v176, v176, v177
	v_max_f32_e32 v64, v176, v176
	v_max_f32_e32 v66, 0, v64
	v_exp_f32_e64 v176, -v66
	v_add_f32_e32 v173, v173, v66
	v_xor_b32_e32 v64, 0x80000000, v173
	v_pk_add_f32 v[96:97], v[96:97], v[66:67] op_sel_hi:[1,0] neg_lo:[0,1] neg_hi:[0,1]
	v_pk_add_f32 v[80:81], v[80:81], v[66:67] op_sel_hi:[1,0] neg_lo:[0,1] neg_hi:[0,1]
	v_pk_add_f32 v[98:99], v[98:99], v[66:67] op_sel_hi:[1,0] neg_lo:[0,1] neg_hi:[0,1]
	v_pk_add_f32 v[82:83], v[82:83], v[66:67] op_sel_hi:[1,0] neg_lo:[0,1] neg_hi:[0,1]
	v_pk_add_f32 v[100:101], v[100:101], v[66:67] op_sel_hi:[1,0] neg_lo:[0,1] neg_hi:[0,1]
	v_pk_add_f32 v[84:85], v[84:85], v[66:67] op_sel_hi:[1,0] neg_lo:[0,1] neg_hi:[0,1]
	v_pk_add_f32 v[102:103], v[102:103], v[66:67] op_sel_hi:[1,0] neg_lo:[0,1] neg_hi:[0,1]
	v_pk_add_f32 v[86:87], v[86:87], v[66:67] op_sel_hi:[1,0] neg_lo:[0,1] neg_hi:[0,1]
	v_pk_add_f32 v[104:105], v[104:105], v[66:67] op_sel_hi:[1,0] neg_lo:[0,1] neg_hi:[0,1]
	v_pk_add_f32 v[88:89], v[88:89], v[66:67] op_sel_hi:[1,0] neg_lo:[0,1] neg_hi:[0,1]
	v_pk_add_f32 v[106:107], v[106:107], v[66:67] op_sel_hi:[1,0] neg_lo:[0,1] neg_hi:[0,1]
	v_pk_add_f32 v[90:91], v[90:91], v[66:67] op_sel_hi:[1,0] neg_lo:[0,1] neg_hi:[0,1]
	v_pk_add_f32 v[108:109], v[108:109], v[66:67] op_sel_hi:[1,0] neg_lo:[0,1] neg_hi:[0,1]
	v_pk_add_f32 v[92:93], v[92:93], v[66:67] op_sel_hi:[1,0] neg_lo:[0,1] neg_hi:[0,1]
	v_pk_add_f32 v[110:111], v[110:111], v[66:67] op_sel_hi:[1,0] neg_lo:[0,1] neg_hi:[0,1]
	v_pk_add_f32 v[94:95], v[94:95], v[66:67] op_sel_hi:[1,0] neg_lo:[0,1] neg_hi:[0,1]
	v_mov_b32_e32 v65, v64
	v_mov_b32_e32 v66, v64
	v_mov_b32_e32 v67, v64
	v_mov_b32_e32 v68, v64
	v_mov_b32_e32 v69, v64
	v_mov_b32_e32 v70, v64
	v_mov_b32_e32 v71, v64
	v_mov_b32_e32 v72, v64
	v_mov_b32_e32 v73, v64
	v_mov_b32_e32 v74, v64
	v_mov_b32_e32 v75, v64
	v_mov_b32_e32 v76, v64
	v_mov_b32_e32 v77, v64
	v_mov_b32_e32 v78, v64
	v_mov_b32_e32 v79, v64
	v_pk_mul_f32 v[46:47], v[46:47], v[176:177] op_sel_hi:[1,0]
	v_pk_mul_f32 v[44:45], v[44:45], v[176:177] op_sel_hi:[1,0]
	v_pk_mul_f32 v[42:43], v[42:43], v[176:177] op_sel_hi:[1,0]
	v_pk_mul_f32 v[40:41], v[40:41], v[176:177] op_sel_hi:[1,0]
	v_pk_mul_f32 v[38:39], v[38:39], v[176:177] op_sel_hi:[1,0]
	v_pk_mul_f32 v[36:37], v[36:37], v[176:177] op_sel_hi:[1,0]
	v_pk_mul_f32 v[34:35], v[34:35], v[176:177] op_sel_hi:[1,0]
	v_pk_mul_f32 v[32:33], v[32:33], v[176:177] op_sel_hi:[1,0]
	v_pk_mul_f32 v[30:31], v[30:31], v[176:177] op_sel_hi:[1,0]
	v_pk_mul_f32 v[28:29], v[28:29], v[176:177] op_sel_hi:[1,0]
	v_pk_mul_f32 v[26:27], v[26:27], v[176:177] op_sel_hi:[1,0]
	v_pk_mul_f32 v[24:25], v[24:25], v[176:177] op_sel_hi:[1,0]
	v_pk_mul_f32 v[22:23], v[22:23], v[176:177] op_sel_hi:[1,0]
	v_pk_mul_f32 v[20:21], v[20:21], v[176:177] op_sel_hi:[1,0]
	v_pk_mul_f32 v[18:19], v[18:19], v[176:177] op_sel_hi:[1,0]
	v_pk_mul_f32 v[16:17], v[16:17], v[176:177] op_sel_hi:[1,0]
	v_pk_mul_f32 v[14:15], v[14:15], v[176:177] op_sel_hi:[1,0]
	v_pk_mul_f32 v[12:13], v[12:13], v[176:177] op_sel_hi:[1,0]
	v_pk_mul_f32 v[10:11], v[10:11], v[176:177] op_sel_hi:[1,0]
	v_pk_mul_f32 v[8:9], v[8:9], v[176:177] op_sel_hi:[1,0]
	v_pk_mul_f32 v[6:7], v[6:7], v[176:177] op_sel_hi:[1,0]
	v_pk_mul_f32 v[4:5], v[4:5], v[176:177] op_sel_hi:[1,0]
	v_pk_mul_f32 v[2:3], v[2:3], v[176:177] op_sel_hi:[1,0]
	v_pk_mul_f32 v[0:1], v[0:1], v[176:177] op_sel_hi:[1,0]
	v_pk_mul_f32 v[62:63], v[62:63], v[176:177] op_sel_hi:[1,0]
	v_pk_mul_f32 v[60:61], v[60:61], v[176:177] op_sel_hi:[1,0]
	v_pk_mul_f32 v[58:59], v[58:59], v[176:177] op_sel_hi:[1,0]
	v_pk_mul_f32 v[56:57], v[56:57], v[176:177] op_sel_hi:[1,0]
	v_pk_mul_f32 v[54:55], v[54:55], v[176:177] op_sel_hi:[1,0]
	v_pk_mul_f32 v[52:53], v[52:53], v[176:177] op_sel_hi:[1,0]
	v_pk_mul_f32 v[50:51], v[50:51], v[176:177] op_sel_hi:[1,0]
	v_pk_mul_f32 v[48:49], v[48:49], v[176:177] op_sel_hi:[1,0]
	v_mul_f32_e32 v172, v172, v176
	v_pk_mul_f32 v[136:137], v[136:137], v[176:177] op_sel_hi:[1,0]
	v_pk_mul_f32 v[138:139], v[138:139], v[176:177] op_sel_hi:[1,0]
	v_pk_mul_f32 v[140:141], v[140:141], v[176:177] op_sel_hi:[1,0]
	v_pk_mul_f32 v[142:143], v[142:143], v[176:177] op_sel_hi:[1,0]
	s_branch .Latt_af1_exp
.Lrs_af2:
	v_mov_b32_e32 v177, v176
	s_nop 1
	v_permlane32_swap_b32_e32 v176, v177
	v_max_f32_e32 v176, v176, v177
	v_max_f32_e32 v64, v176, v176
	v_max_f32_e32 v66, 0, v64
	v_exp_f32_e64 v176, -v66
	v_add_f32_e32 v173, v173, v66
	v_xor_b32_e32 v64, 0x80000000, v173
	v_pk_add_f32 v[96:97], v[96:97], v[66:67] op_sel_hi:[1,0] neg_lo:[0,1] neg_hi:[0,1]
	v_pk_add_f32 v[80:81], v[80:81], v[66:67] op_sel_hi:[1,0] neg_lo:[0,1] neg_hi:[0,1]
	v_pk_add_f32 v[98:99], v[98:99], v[66:67] op_sel_hi:[1,0] neg_lo:[0,1] neg_hi:[0,1]
	v_pk_add_f32 v[82:83], v[82:83], v[66:67] op_sel_hi:[1,0] neg_lo:[0,1] neg_hi:[0,1]
	v_pk_add_f32 v[100:101], v[100:101], v[66:67] op_sel_hi:[1,0] neg_lo:[0,1] neg_hi:[0,1]
	v_pk_add_f32 v[84:85], v[84:85], v[66:67] op_sel_hi:[1,0] neg_lo:[0,1] neg_hi:[0,1]
	v_pk_add_f32 v[102:103], v[102:103], v[66:67] op_sel_hi:[1,0] neg_lo:[0,1] neg_hi:[0,1]
	v_pk_add_f32 v[86:87], v[86:87], v[66:67] op_sel_hi:[1,0] neg_lo:[0,1] neg_hi:[0,1]
	v_pk_add_f32 v[104:105], v[104:105], v[66:67] op_sel_hi:[1,0] neg_lo:[0,1] neg_hi:[0,1]
	v_pk_add_f32 v[88:89], v[88:89], v[66:67] op_sel_hi:[1,0] neg_lo:[0,1] neg_hi:[0,1]
	v_pk_add_f32 v[106:107], v[106:107], v[66:67] op_sel_hi:[1,0] neg_lo:[0,1] neg_hi:[0,1]
	v_pk_add_f32 v[90:91], v[90:91], v[66:67] op_sel_hi:[1,0] neg_lo:[0,1] neg_hi:[0,1]
	v_pk_add_f32 v[108:109], v[108:109], v[66:67] op_sel_hi:[1,0] neg_lo:[0,1] neg_hi:[0,1]
	v_pk_add_f32 v[92:93], v[92:93], v[66:67] op_sel_hi:[1,0] neg_lo:[0,1] neg_hi:[0,1]
	v_pk_add_f32 v[110:111], v[110:111], v[66:67] op_sel_hi:[1,0] neg_lo:[0,1] neg_hi:[0,1]
	v_pk_add_f32 v[94:95], v[94:95], v[66:67] op_sel_hi:[1,0] neg_lo:[0,1] neg_hi:[0,1]
	v_mov_b32_e32 v65, v64
	v_mov_b32_e32 v66, v64
	v_mov_b32_e32 v67, v64
	v_mov_b32_e32 v68, v64
	v_mov_b32_e32 v69, v64
	v_mov_b32_e32 v70, v64
	v_mov_b32_e32 v71, v64
	v_mov_b32_e32 v72, v64
	v_mov_b32_e32 v73, v64
	v_mov_b32_e32 v74, v64
	v_mov_b32_e32 v75, v64
	v_mov_b32_e32 v76, v64
	v_mov_b32_e32 v77, v64
	v_mov_b32_e32 v78, v64
	v_mov_b32_e32 v79, v64
	v_pk_mul_f32 v[46:47], v[46:47], v[176:177] op_sel_hi:[1,0]
	v_pk_mul_f32 v[44:45], v[44:45], v[176:177] op_sel_hi:[1,0]
	v_pk_mul_f32 v[42:43], v[42:43], v[176:177] op_sel_hi:[1,0]
	v_pk_mul_f32 v[40:41], v[40:41], v[176:177] op_sel_hi:[1,0]
	v_pk_mul_f32 v[38:39], v[38:39], v[176:177] op_sel_hi:[1,0]
	v_pk_mul_f32 v[36:37], v[36:37], v[176:177] op_sel_hi:[1,0]
	v_pk_mul_f32 v[34:35], v[34:35], v[176:177] op_sel_hi:[1,0]
	v_pk_mul_f32 v[32:33], v[32:33], v[176:177] op_sel_hi:[1,0]
	v_pk_mul_f32 v[30:31], v[30:31], v[176:177] op_sel_hi:[1,0]
	v_pk_mul_f32 v[28:29], v[28:29], v[176:177] op_sel_hi:[1,0]
	v_pk_mul_f32 v[26:27], v[26:27], v[176:177] op_sel_hi:[1,0]
	v_pk_mul_f32 v[24:25], v[24:25], v[176:177] op_sel_hi:[1,0]
	v_pk_mul_f32 v[22:23], v[22:23], v[176:177] op_sel_hi:[1,0]
	v_pk_mul_f32 v[20:21], v[20:21], v[176:177] op_sel_hi:[1,0]
	v_pk_mul_f32 v[18:19], v[18:19], v[176:177] op_sel_hi:[1,0]
	v_pk_mul_f32 v[16:17], v[16:17], v[176:177] op_sel_hi:[1,0]
	v_pk_mul_f32 v[14:15], v[14:15], v[176:177] op_sel_hi:[1,0]
	v_pk_mul_f32 v[12:13], v[12:13], v[176:177] op_sel_hi:[1,0]
	v_pk_mul_f32 v[10:11], v[10:11], v[176:177] op_sel_hi:[1,0]
	v_pk_mul_f32 v[8:9], v[8:9], v[176:177] op_sel_hi:[1,0]
	v_pk_mul_f32 v[6:7], v[6:7], v[176:177] op_sel_hi:[1,0]
	v_pk_mul_f32 v[4:5], v[4:5], v[176:177] op_sel_hi:[1,0]
	v_pk_mul_f32 v[2:3], v[2:3], v[176:177] op_sel_hi:[1,0]
	v_pk_mul_f32 v[0:1], v[0:1], v[176:177] op_sel_hi:[1,0]
	v_pk_mul_f32 v[62:63], v[62:63], v[176:177] op_sel_hi:[1,0]
	v_pk_mul_f32 v[60:61], v[60:61], v[176:177] op_sel_hi:[1,0]
	v_pk_mul_f32 v[58:59], v[58:59], v[176:177] op_sel_hi:[1,0]
	v_pk_mul_f32 v[56:57], v[56:57], v[176:177] op_sel_hi:[1,0]
	v_pk_mul_f32 v[54:55], v[54:55], v[176:177] op_sel_hi:[1,0]
	v_pk_mul_f32 v[52:53], v[52:53], v[176:177] op_sel_hi:[1,0]
	v_pk_mul_f32 v[50:51], v[50:51], v[176:177] op_sel_hi:[1,0]
	v_pk_mul_f32 v[48:49], v[48:49], v[176:177] op_sel_hi:[1,0]
	v_mul_f32_e32 v172, v172, v176
	v_pk_mul_f32 v[136:137], v[136:137], v[176:177] op_sel_hi:[1,0]
	v_pk_mul_f32 v[138:139], v[138:139], v[176:177] op_sel_hi:[1,0]
	v_pk_mul_f32 v[140:141], v[140:141], v[176:177] op_sel_hi:[1,0]
	v_pk_mul_f32 v[142:143], v[142:143], v[176:177] op_sel_hi:[1,0]
	s_branch .Latt_af2_exp
.Lrs_af0:
	v_mov_b32_e32 v177, v176
	s_nop 1
	v_permlane32_swap_b32_e32 v176, v177
	v_max_f32_e32 v176, v176, v177
	v_max_f32_e32 v64, v176, v176
	v_max_f32_e32 v66, 0, v64
	v_exp_f32_e64 v176, -v66
	v_add_f32_e32 v173, v173, v66
	v_xor_b32_e32 v64, 0x80000000, v173
	v_pk_add_f32 v[96:97], v[96:97], v[66:67] op_sel_hi:[1,0] neg_lo:[0,1] neg_hi:[0,1]
	v_pk_add_f32 v[80:81], v[80:81], v[66:67] op_sel_hi:[1,0] neg_lo:[0,1] neg_hi:[0,1]
	v_pk_add_f32 v[98:99], v[98:99], v[66:67] op_sel_hi:[1,0] neg_lo:[0,1] neg_hi:[0,1]
	v_pk_add_f32 v[82:83], v[82:83], v[66:67] op_sel_hi:[1,0] neg_lo:[0,1] neg_hi:[0,1]
	v_pk_add_f32 v[100:101], v[100:101], v[66:67] op_sel_hi:[1,0] neg_lo:[0,1] neg_hi:[0,1]
	v_pk_add_f32 v[84:85], v[84:85], v[66:67] op_sel_hi:[1,0] neg_lo:[0,1] neg_hi:[0,1]
	v_pk_add_f32 v[102:103], v[102:103], v[66:67] op_sel_hi:[1,0] neg_lo:[0,1] neg_hi:[0,1]
	v_pk_add_f32 v[86:87], v[86:87], v[66:67] op_sel_hi:[1,0] neg_lo:[0,1] neg_hi:[0,1]
	v_pk_add_f32 v[104:105], v[104:105], v[66:67] op_sel_hi:[1,0] neg_lo:[0,1] neg_hi:[0,1]
	v_pk_add_f32 v[88:89], v[88:89], v[66:67] op_sel_hi:[1,0] neg_lo:[0,1] neg_hi:[0,1]
	v_pk_add_f32 v[106:107], v[106:107], v[66:67] op_sel_hi:[1,0] neg_lo:[0,1] neg_hi:[0,1]
	v_pk_add_f32 v[90:91], v[90:91], v[66:67] op_sel_hi:[1,0] neg_lo:[0,1] neg_hi:[0,1]
	v_pk_add_f32 v[108:109], v[108:109], v[66:67] op_sel_hi:[1,0] neg_lo:[0,1] neg_hi:[0,1]
	v_pk_add_f32 v[92:93], v[92:93], v[66:67] op_sel_hi:[1,0] neg_lo:[0,1] neg_hi:[0,1]
	v_pk_add_f32 v[110:111], v[110:111], v[66:67] op_sel_hi:[1,0] neg_lo:[0,1] neg_hi:[0,1]
	v_pk_add_f32 v[94:95], v[94:95], v[66:67] op_sel_hi:[1,0] neg_lo:[0,1] neg_hi:[0,1]
	v_mov_b32_e32 v65, v64
	v_mov_b32_e32 v66, v64
	v_mov_b32_e32 v67, v64
	v_mov_b32_e32 v68, v64
	v_mov_b32_e32 v69, v64
	v_mov_b32_e32 v70, v64
	v_mov_b32_e32 v71, v64
	v_mov_b32_e32 v72, v64
	v_mov_b32_e32 v73, v64
	v_mov_b32_e32 v74, v64
	v_mov_b32_e32 v75, v64
	v_mov_b32_e32 v76, v64
	v_mov_b32_e32 v77, v64
	v_mov_b32_e32 v78, v64
	v_mov_b32_e32 v79, v64
	v_pk_mul_f32 v[46:47], v[46:47], v[176:177] op_sel_hi:[1,0]
	v_pk_mul_f32 v[44:45], v[44:45], v[176:177] op_sel_hi:[1,0]
	v_pk_mul_f32 v[42:43], v[42:43], v[176:177] op_sel_hi:[1,0]
	v_pk_mul_f32 v[40:41], v[40:41], v[176:177] op_sel_hi:[1,0]
	v_pk_mul_f32 v[38:39], v[38:39], v[176:177] op_sel_hi:[1,0]
	v_pk_mul_f32 v[36:37], v[36:37], v[176:177] op_sel_hi:[1,0]
	v_pk_mul_f32 v[34:35], v[34:35], v[176:177] op_sel_hi:[1,0]
	v_pk_mul_f32 v[32:33], v[32:33], v[176:177] op_sel_hi:[1,0]
	v_pk_mul_f32 v[30:31], v[30:31], v[176:177] op_sel_hi:[1,0]
	v_pk_mul_f32 v[28:29], v[28:29], v[176:177] op_sel_hi:[1,0]
	v_pk_mul_f32 v[26:27], v[26:27], v[176:177] op_sel_hi:[1,0]
	v_pk_mul_f32 v[24:25], v[24:25], v[176:177] op_sel_hi:[1,0]
	v_pk_mul_f32 v[22:23], v[22:23], v[176:177] op_sel_hi:[1,0]
	v_pk_mul_f32 v[20:21], v[20:21], v[176:177] op_sel_hi:[1,0]
	v_pk_mul_f32 v[18:19], v[18:19], v[176:177] op_sel_hi:[1,0]
	v_pk_mul_f32 v[16:17], v[16:17], v[176:177] op_sel_hi:[1,0]
	v_pk_mul_f32 v[14:15], v[14:15], v[176:177] op_sel_hi:[1,0]
	v_pk_mul_f32 v[12:13], v[12:13], v[176:177] op_sel_hi:[1,0]
	v_pk_mul_f32 v[10:11], v[10:11], v[176:177] op_sel_hi:[1,0]
	v_pk_mul_f32 v[8:9], v[8:9], v[176:177] op_sel_hi:[1,0]
	v_pk_mul_f32 v[6:7], v[6:7], v[176:177] op_sel_hi:[1,0]
	v_pk_mul_f32 v[4:5], v[4:5], v[176:177] op_sel_hi:[1,0]
	v_pk_mul_f32 v[2:3], v[2:3], v[176:177] op_sel_hi:[1,0]
	v_pk_mul_f32 v[0:1], v[0:1], v[176:177] op_sel_hi:[1,0]
	v_pk_mul_f32 v[62:63], v[62:63], v[176:177] op_sel_hi:[1,0]
	v_pk_mul_f32 v[60:61], v[60:61], v[176:177] op_sel_hi:[1,0]
	v_pk_mul_f32 v[58:59], v[58:59], v[176:177] op_sel_hi:[1,0]
	v_pk_mul_f32 v[56:57], v[56:57], v[176:177] op_sel_hi:[1,0]
	v_pk_mul_f32 v[54:55], v[54:55], v[176:177] op_sel_hi:[1,0]
	v_pk_mul_f32 v[52:53], v[52:53], v[176:177] op_sel_hi:[1,0]
	v_pk_mul_f32 v[50:51], v[50:51], v[176:177] op_sel_hi:[1,0]
	v_pk_mul_f32 v[48:49], v[48:49], v[176:177] op_sel_hi:[1,0]
	v_mul_f32_e32 v172, v172, v176
	v_pk_mul_f32 v[136:137], v[136:137], v[176:177] op_sel_hi:[1,0]
	v_pk_mul_f32 v[138:139], v[138:139], v[176:177] op_sel_hi:[1,0]
	v_pk_mul_f32 v[140:141], v[140:141], v[176:177] op_sel_hi:[1,0]
	v_pk_mul_f32 v[142:143], v[142:143], v[176:177] op_sel_hi:[1,0]
	s_branch .Latt_af0_exp
.Lba_a1:
	s_lshl_b32 s68, s65, 8
	s_addk_i32 s68, 0xfd00
	s_waitcnt lgkmcnt(0)
	v_add_u32_e32 v205, s68, v204
	v_add_u32_e32 v176, 0x17d00, v205
	v_add_u32_e32 v178, 0x17d80, v205
	ds_read2_b32 v[176:177], v176 offset1:1
	ds_read2_b32 v[178:179], v178 offset1:1
	v_add_u32_e32 v180, 0x17d08, v205
	v_add_u32_e32 v182, 0x17d88, v205
	v_add_u32_e32 v184, 0x17d20, v205
	v_add_u32_e32 v186, 0x17da0, v205
	v_add_u32_e32 v188, 0x17d28, v205
	v_add_u32_e32 v190, 0x17da8, v205
	v_add_u32_e32 v206, 0x17d40, v205
	v_add_u32_e32 v210, 0x17dc0, v205
	v_add_u32_e32 v212, 0x17d48, v205
	v_add_u32_e32 v221, 0x17dc8, v205
	ds_read2_b32 v[180:181], v180 offset1:1
	ds_read2_b32 v[182:183], v182 offset1:1
	ds_read2_b32 v[184:185], v184 offset1:1
	ds_read2_b32 v[186:187], v186 offset1:1
	ds_read2_b32 v[188:189], v188 offset1:1
	ds_read2_b32 v[190:191], v190 offset1:1
	ds_read2_b32 v[206:207], v206 offset1:1
	ds_read2_b32 v[210:211], v210 offset1:1
	ds_read2_b32 v[212:213], v212 offset1:1
	ds_read2_b32 v[224:225], v221 offset1:1
	v_add_u32_e32 v221, 0x17d60, v205
	v_add_u32_e32 v223, 0x17de0, v205
	ds_read2_b32 v[226:227], v221 offset1:1
	ds_read2_b32 v[228:229], v223 offset1:1
	v_add_u32_e32 v221, 0x17d68, v205
	v_add_u32_e32 v205, 0x17de8, v205
	ds_read2_b32 v[230:231], v221 offset1:1
	s_waitcnt lgkmcnt(14)
	v_pk_add_f32 v[96:97], v[96:97], v[176:177]
	ds_read2_b32 v[176:177], v205 offset1:1
	s_waitcnt lgkmcnt(3)
	v_pk_add_f32 v[108:109], v[108:109], v[226:227]
	v_pk_add_f32 v[106:107], v[106:107], v[212:213]
	s_waitcnt lgkmcnt(1)
	v_pk_add_f32 v[110:111], v[110:111], v[230:231]
	v_pk_add_f32 v[104:105], v[104:105], v[206:207]
	v_pk_add_f32 v[102:103], v[102:103], v[188:189]
	v_pk_add_f32 v[100:101], v[100:101], v[184:185]
	v_pk_add_f32 v[98:99], v[98:99], v[180:181]
	s_waitcnt lgkmcnt(0)
	v_pk_add_f32 v[94:95], v[94:95], v[176:177]
	v_pk_add_f32 v[92:93], v[92:93], v[228:229]
	v_pk_add_f32 v[90:91], v[90:91], v[224:225]
	v_pk_add_f32 v[88:89], v[88:89], v[210:211]
	v_pk_add_f32 v[86:87], v[86:87], v[190:191]
	v_pk_add_f32 v[84:85], v[84:85], v[186:187]
	v_pk_add_f32 v[82:83], v[82:83], v[182:183]
	v_pk_add_f32 v[80:81], v[80:81], v[178:179]
	s_nop 0
	s_branch .Latt_a1_stg

.Lisl_11:
	s_branch .LBB0_11
.LBB0_243:
	v_pk_add_f32 v[136:137], v[136:137], v[138:139]
	v_pk_add_f32 v[140:141], v[140:141], v[142:143]
	s_nop 0
	v_pk_add_f32 v[136:137], v[136:137], v[140:141]
	s_nop 0
	v_add_f32_e32 v136, v136, v137
	v_add_f32_e32 v172, v172, v136
	s_and_b64 vcc, exec, s[16:17]
	s_cbranch_vccz .LBB0_245
	s_mul_i32 s4, s69, 0x5000
	v_add_u32_e32 v96, s4, v165
	ds_read_b64_tr_b16 v[64:65], v96 offset:34816
	ds_read_b64_tr_b16 v[66:67], v96 offset:37376
	ds_read_b64_tr_b16 v[68:69], v96 offset:39936
	ds_read_b64_tr_b16 v[70:71], v96 offset:42496
	ds_read_b64_tr_b16 v[72:73], v96 offset:45056
	ds_read_b64_tr_b16 v[74:75], v96 offset:47616
	ds_read_b64_tr_b16 v[76:77], v96 offset:50176
	ds_read_b64_tr_b16 v[78:79], v96 offset:52736
	s_setprio 1
	s_waitcnt lgkmcnt(6)
	v_mfma_f32_32x32x16_bf16 v[32:47], v[64:67], v[80:83], v[32:47]
	s_setprio 0
	ds_read_b64_tr_b16 v[64:65], v96 offset:34880
	ds_read_b64_tr_b16 v[66:67], v96 offset:37440
	s_setprio 1
	s_waitcnt lgkmcnt(6)
	v_mfma_f32_32x32x16_bf16 v[32:47], v[68:71], v[84:87], v[32:47]
	s_setprio 0
	ds_read_b64_tr_b16 v[68:69], v96 offset:40000
	ds_read_b64_tr_b16 v[70:71], v96 offset:42560
	s_setprio 1
	s_waitcnt lgkmcnt(6)
	v_mfma_f32_32x32x16_bf16 v[32:47], v[72:75], v[88:91], v[32:47]
	s_setprio 0
	ds_read_b64_tr_b16 v[72:73], v96 offset:45120
	ds_read_b64_tr_b16 v[74:75], v96 offset:47680
	s_setprio 1
	s_waitcnt lgkmcnt(6)
	v_mfma_f32_32x32x16_bf16 v[32:47], v[76:79], v[92:95], v[32:47]
	s_setprio 0
	ds_read_b64_tr_b16 v[76:77], v96 offset:50240
	ds_read_b64_tr_b16 v[78:79], v96 offset:52800
	s_setprio 1
	s_waitcnt lgkmcnt(6)
	v_mfma_f32_32x32x16_bf16 v[16:31], v[64:67], v[80:83], v[16:31]
	s_setprio 0
	ds_read_b64_tr_b16 v[64:65], v96 offset:34944
	ds_read_b64_tr_b16 v[66:67], v96 offset:37504
	s_setprio 1
	s_waitcnt lgkmcnt(6)
	v_mfma_f32_32x32x16_bf16 v[16:31], v[68:71], v[84:87], v[16:31]
	s_setprio 0
	ds_read_b64_tr_b16 v[68:69], v96 offset:40064
	ds_read_b64_tr_b16 v[70:71], v96 offset:42624
	s_setprio 1
	s_waitcnt lgkmcnt(6)
	v_mfma_f32_32x32x16_bf16 v[16:31], v[72:75], v[88:91], v[16:31]
	s_setprio 0
	ds_read_b64_tr_b16 v[72:73], v96 offset:45184
	ds_read_b64_tr_b16 v[74:75], v96 offset:47744
	s_setprio 1
	s_waitcnt lgkmcnt(6)
	v_mfma_f32_32x32x16_bf16 v[16:31], v[76:79], v[92:95], v[16:31]
	s_setprio 0
	ds_read_b64_tr_b16 v[76:77], v96 offset:50304
	ds_read_b64_tr_b16 v[78:79], v96 offset:52864
	s_setprio 1
	s_waitcnt lgkmcnt(6)
	v_mfma_f32_32x32x16_bf16 v[0:15], v[64:67], v[80:83], v[0:15]
	s_setprio 0
	ds_read_b64_tr_b16 v[64:65], v96 offset:35008
	ds_read_b64_tr_b16 v[66:67], v96 offset:37568
	s_setprio 1
	s_waitcnt lgkmcnt(6)
	v_mfma_f32_32x32x16_bf16 v[0:15], v[68:71], v[84:87], v[0:15]
	s_setprio 0
	ds_read_b64_tr_b16 v[68:69], v96 offset:40128
	ds_read_b64_tr_b16 v[70:71], v96 offset:42688
	s_setprio 1
	s_waitcnt lgkmcnt(6)
	v_mfma_f32_32x32x16_bf16 v[0:15], v[72:75], v[88:91], v[0:15]
	s_setprio 0
	ds_read_b64_tr_b16 v[72:73], v96 offset:45248
	ds_read_b64_tr_b16 v[74:75], v96 offset:47808
	s_setprio 1
	s_waitcnt lgkmcnt(6)
	v_mfma_f32_32x32x16_bf16 v[0:15], v[76:79], v[92:95], v[0:15]
	s_setprio 0
	ds_read_b64_tr_b16 v[76:77], v96 offset:50368
	ds_read_b64_tr_b16 v[78:79], v96 offset:52928
	s_setprio 1
	s_waitcnt lgkmcnt(6)
	v_mfma_f32_32x32x16_bf16 v[48:63], v[64:67], v[80:83], v[48:63]
	s_setprio 0
	s_setprio 1
	s_waitcnt lgkmcnt(4)
	v_mfma_f32_32x32x16_bf16 v[48:63], v[68:71], v[84:87], v[48:63]
	s_setprio 0
	s_setprio 1
	s_waitcnt lgkmcnt(2)
	v_mfma_f32_32x32x16_bf16 v[48:63], v[72:75], v[88:91], v[48:63]
	s_setprio 0
	s_setprio 1
	s_waitcnt lgkmcnt(0)
	v_mfma_f32_32x32x16_bf16 v[48:63], v[76:79], v[92:95], v[48:63]
	s_setprio 0
